# v93 + GLA in-chunk cumsum quad offsets via permlane swaps (inside the full stack)
# speedup vs baseline: 1.0022x; 1.0022x over previous
.LBB0_469:
	v_mov_b32_e32 v244, v183
	v_mov_b32_e32 v245, v183
	s_nop 1
	v_permlane16_swap_b32_e32 v244, v245
	v_mov_b32_e32 v246, v244
	v_mov_b32_e32 v247, v245
	s_nop 1
	v_permlane32_swap_b32_e32 v244, v246
	v_permlane32_swap_b32_e32 v245, v247
	v_mov_b32_e32 v96, v244
	v_mov_b32_e32 v97, v245
	v_mov_b32_e32 v95, v246
	v_mov_b32_e32 v98, v247
	s_mov_b64 s[52:53], -1
	s_and_b64 vcc, exec, s[48:49]
	s_cbranch_vccz .LBB0_471
	s_waitcnt lgkmcnt(0)
	v_cndmask_b32_e64 v94, v98, 0, s[6:7]
	v_cndmask_b32_e64 v98, 0, v95, s[8:9]
	v_add_f32_e32 v94, v98, v94
	v_cndmask_b32_e64 v98, 0, v97, s[10:11]
	v_add_f32_e32 v94, v98, v94
	s_mov_b64 s[52:53], 0

.LBB0_484:
	v_mov_b32_e32 v244, v174
	v_mov_b32_e32 v245, v174
	s_nop 1
	v_permlane16_swap_b32_e32 v244, v245
	v_mov_b32_e32 v246, v244
	v_mov_b32_e32 v247, v245
	s_nop 1
	v_permlane32_swap_b32_e32 v244, v246
	v_permlane32_swap_b32_e32 v245, v247
	v_mov_b32_e32 v92, v244
	v_mov_b32_e32 v93, v245
	v_mov_b32_e32 v91, v246
	v_mov_b32_e32 v94, v247
	s_and_b64 vcc, exec, s[30:31]
	s_mov_b64 s[30:31], -1
	s_cbranch_vccnz .LBB0_486
	s_waitcnt lgkmcnt(0)
	v_cndmask_b32_e64 v90, v94, 0, s[6:7]
	v_cndmask_b32_e64 v94, 0, v91, s[8:9]
	v_add_f32_e32 v90, v94, v90
	v_cndmask_b32_e64 v94, 0, v93, s[10:11]
	v_add_f32_e32 v90, v94, v90
	s_mov_b64 s[30:31], 0

.LBB0_502:
	s_add_u32 s50, s53, s46
	s_addc_u32 s51, s77, s47
	s_add_u32 s31, s43, s46
	s_addc_u32 s48, s52, s47
	s_add_u32 s80, s31, s76
	s_addc_u32 s81, s48, 0
	s_and_b32 s79, s78, 1
	s_cmp_eq_u32 s79, 0
	s_cselect_b64 s[48:49], -1, 0
	s_and_b64 s[82:83], s[48:49], exec
	s_cselect_b32 s31, 0xf0, s67
	v_and_b32_e32 v1, 63, v154
	v_lshl_add_u32 v1, v1, 2, s31
	ds_read2st64_b32 v[74:75], v1 offset1:1
	v_lshl_add_u64 v[76:77], s[50:51], 0, v[112:113]
	ds_read2st64_b32 v[82:83], v1 offset0:4 offset1:5
	global_load_dwordx4 v[94:97], v[76:77], off
	global_load_dwordx4 v[98:101], v[76:77], off offset:1024
	ds_read2st64_b32 v[108:109], v1 offset0:2 offset1:3
	v_lshl_add_u64 v[84:85], s[80:81], 0, v[114:115]
	s_mov_b32 s31, 0x3d800000
	s_waitcnt vmcnt(6) lgkmcnt(2)
	v_mfma_f32_16x16x4_f32 v[70:73], v74, v102, 0
	v_add_co_u32_e32 v74, vcc, s63, v76
	s_waitcnt vmcnt(5)
	v_mfma_f32_16x16x4_f32 v[70:73], v75, v103, v[70:73]
	v_addc_co_u32_e32 v75, vcc, 0, v77, vcc
	global_load_dwordx4 v[86:89], v[74:75], off
	global_load_dwordx4 v[90:93], v[74:75], off offset:1024
	v_add_co_u32_e32 v74, vcc, s64, v84
	s_nop 1
	v_addc_co_u32_e32 v75, vcc, 0, v85, vcc
	s_waitcnt vmcnt(6) lgkmcnt(0)
	v_mfma_f32_16x16x4_f32 v[160:163], v108, v104, v[70:73]
	v_add_co_u32_e32 v168, vcc, s63, v84
	global_load_dwordx4 v[70:73], v[84:85], off
	s_nop 0
	global_load_dwordx4 v[74:77], v[74:75], off
	v_addc_co_u32_e32 v169, vcc, 0, v85, vcc
	v_mfma_f32_16x16x4_f32 v[78:81], v82, v102, 0
	v_add_co_u32_e32 v82, vcc, s65, v84
	s_waitcnt vmcnt(7)
	v_mfma_f32_16x16x4_f32 v[160:163], v109, v105, v[160:163]
	v_mfma_f32_16x16x4_f32 v[164:167], v83, v103, v[78:81]
	v_addc_co_u32_e32 v83, vcc, 0, v85, vcc
	s_nop 4
	global_load_dwordx4 v[78:81], v[168:169], off
	s_nop 0
	global_load_dwordx4 v[82:85], v[82:83], off
	ds_read2st64_b32 v[168:169], v1 offset0:6 offset1:7
	s_waitcnt vmcnt(8)
	v_add_f32_e32 v107, v106, v160
	v_min_f32_e32 v170, 0, v107
	v_mul_f32_e64 v107, |v107|, s68
	v_exp_f32_e32 v107, v107
	v_add_f32_e32 v108, v106, v161
	v_add_f32_e32 v109, v106, v162
	v_mul_f32_e64 v160, |v108|, s68
	v_mul_f32_e64 v161, |v109|, s68
	v_exp_f32_e32 v160, v160
	v_exp_f32_e32 v161, v161
	v_add_f32_e32 v107, 1.0, v107
	v_log_f32_e32 v107, v107
	s_waitcnt lgkmcnt(0)
	v_mfma_f32_16x16x4_f32 v[164:167], v168, v104, v[164:167]
	v_add_f32_e32 v160, 1.0, v160
	v_add_f32_e32 v161, 1.0, v161
	v_log_f32_e32 v160, v160
	v_fmac_f32_e32 v170, 0xbf317218, v107
	v_log_f32_e32 v107, v161
	v_min_f32_e32 v171, 0, v108
	v_min_f32_e32 v172, 0, v109
	v_fmac_f32_e32 v171, 0xbf317218, v160
	v_fmac_f32_e32 v172, 0xbf317218, v107
	v_add_f32_e32 v107, v106, v163
	v_mfma_f32_16x16x4_f32 v[160:163], v169, v105, v[164:167]
	v_mul_f32_e64 v108, |v107|, s68
	v_exp_f32_e32 v168, v108
	v_min_f32_e32 v107, 0, v107
	v_add_f32_e32 v165, 1.0, v168
	v_log_f32_e32 v165, v165
	s_nop 4
	v_add_f32_e32 v160, v106, v160
	v_mul_f32_e64 v108, |v160|, s68
	v_exp_f32_e32 v164, v108
	ds_read2st64_b32 v[108:109], v1 offset0:8 offset1:9
	v_min_f32_e32 v173, 0, v160
	v_fmac_f32_e32 v107, 0xbf317218, v165
	v_add_f32_e32 v164, 1.0, v164
	v_log_f32_e32 v164, v164
	ds_read2st64_b32 v[168:169], v1 offset0:10 offset1:11
	v_add_f32_e32 v174, v106, v162
	v_add_f32_e32 v176, v106, v163
	v_fmac_f32_e32 v173, 0xbf317218, v164
	s_waitcnt lgkmcnt(1)
	v_mfma_f32_16x16x4_f32 v[164:167], v108, v102, 0
	v_add_f32_e32 v108, v106, v161
	v_mul_f32_e64 v160, |v108|, s68
	v_mul_f32_e64 v161, |v174|, s68
	v_exp_f32_e32 v160, v160
	v_exp_f32_e32 v161, v161
	v_min_f32_e32 v175, 0, v108
	v_mul_f32_e64 v177, |v176|, s68
	v_mfma_f32_16x16x4_f32 v[164:167], v109, v103, v[164:167]
	v_add_f32_e32 v108, 1.0, v160
	v_add_f32_e32 v109, 1.0, v161
	v_log_f32_e32 v108, v108
	v_log_f32_e32 v109, v109
	v_min_f32_e32 v174, 0, v174
	v_min_f32_e32 v176, 0, v176
	v_fmac_f32_e32 v175, 0xbf317218, v108
	s_waitcnt lgkmcnt(0)
	v_mfma_f32_16x16x4_f32 v[160:163], v168, v104, v[164:167]
	s_nop 0
	v_exp_f32_e32 v164, v177
	v_fmac_f32_e32 v174, 0xbf317218, v109
	v_add_f32_e32 v108, 1.0, v164
	v_log_f32_e32 v164, v108
	ds_read2st64_b32 v[108:109], v1 offset0:12 offset1:13
	v_mfma_f32_16x16x4_f32 v[160:163], v169, v105, v[160:163]
	v_fmac_f32_e32 v176, 0xbf317218, v164
	s_nop 8
	v_add_f32_e32 v160, v106, v160
	v_mul_f32_e64 v164, |v160|, s68
	v_exp_f32_e32 v168, v164
	s_waitcnt lgkmcnt(0)
	v_mfma_f32_16x16x4_f32 v[164:167], v108, v102, 0
	v_add_f32_e32 v161, v106, v161
	v_mul_f32_e64 v169, |v161|, s68
	v_exp_f32_e32 v108, v169
	v_min_f32_e32 v177, 0, v160
	v_add_f32_e32 v160, 1.0, v168
	ds_read2st64_b32 v[168:169], v1 offset0:14 offset1:15
	v_add_f32_e32 v108, 1.0, v108
	v_mfma_f32_16x16x4_f32 v[164:167], v109, v103, v[164:167]
	v_log_f32_e32 v160, v160
	v_log_f32_e32 v108, v108
	v_min_f32_e32 v1, 0, v161
	v_add_f32_e32 v178, v106, v163
	v_fmac_f32_e32 v177, 0xbf317218, v160
	v_fmac_f32_e32 v1, 0xbf317218, v108
	v_add_f32_e32 v108, v106, v162
	s_waitcnt lgkmcnt(0)
	v_mfma_f32_16x16x4_f32 v[160:163], v168, v104, v[164:167]
	v_mul_f32_e64 v109, |v108|, s68
	v_exp_f32_e32 v109, v109
	v_mul_f32_e64 v164, |v178|, s68
	v_exp_f32_e32 v164, v164
	v_min_f32_e32 v108, 0, v108
	v_add_f32_e32 v109, 1.0, v109
	v_log_f32_e32 v109, v109
	v_mfma_f32_16x16x4_f32 v[160:163], v169, v105, v[160:163]
	v_add_f32_e32 v164, 1.0, v164
	v_log_f32_e32 v164, v164
	v_fmac_f32_e32 v108, 0xbf317218, v109
	v_min_f32_e32 v109, 0, v178
	v_fmac_f32_e32 v109, 0xbf317218, v164
	s_nop 4
	v_add_f32_e32 v160, v106, v160
	v_mul_f32_e64 v165, |v160|, s68
	v_exp_f32_e32 v165, v165
	v_add_f32_e32 v161, v106, v161
	v_min_f32_e32 v160, 0, v160
	v_add_f32_e32 v162, v106, v162
	v_add_f32_e32 v164, 1.0, v165
	v_mul_f32_e64 v165, |v161|, s68
	v_log_f32_e32 v164, v164
	v_exp_f32_e32 v165, v165
	v_add_f32_e32 v163, v106, v163
	v_mul_f32_e64 v166, |v163|, s68
	v_fmac_f32_e32 v160, 0xbf317218, v164
	v_add_f32_e32 v164, 1.0, v165
	v_mul_f32_e64 v165, |v162|, s68
	v_log_f32_e32 v164, v164
	v_exp_f32_e32 v165, v165
	v_exp_f32_e32 v166, v166
	v_min_f32_e32 v161, 0, v161
	v_fmac_f32_e32 v161, 0xbf317218, v164
	v_add_f32_e32 v164, 1.0, v165
	v_log_f32_e32 v164, v164
	v_add_f32_e32 v165, 1.0, v166
	v_log_f32_e32 v165, v165
	v_min_f32_e32 v162, 0, v162
	v_fmac_f32_e32 v162, 0xbf317218, v164
	v_min_f32_e32 v163, 0, v163
	v_fma_f32 v164, v170, s31, 0
	v_fmac_f32_e32 v163, 0xbf317218, v165
	v_fmamk_f32 v165, v171, 0x3d800000, v164
	v_fmamk_f32 v166, v172, 0x3d800000, v165
	v_fmamk_f32 v107, v107, 0x3d800000, v166
	v_fmamk_f32 v167, v173, 0x3d800000, v107
	v_fmamk_f32 v168, v175, 0x3d800000, v167
	v_fmamk_f32 v169, v174, 0x3d800000, v168
	v_fmamk_f32 v170, v176, 0x3d800000, v169
	v_fmamk_f32 v171, v177, 0x3d800000, v170
	v_fmamk_f32 v1, v1, 0x3d800000, v171
	v_fmamk_f32 v108, v108, 0x3d800000, v1
	v_fmamk_f32 v109, v109, 0x3d800000, v108
	v_fmamk_f32 v160, v160, 0x3d800000, v109
	v_fmamk_f32 v161, v161, 0x3d800000, v160
	v_fmamk_f32 v162, v162, 0x3d800000, v161
	v_fmamk_f32 v163, v163, 0x3d800000, v162
	v_mov_b32_e32 v244, v163
	v_mov_b32_e32 v245, v163
	s_nop 1
	v_permlane16_swap_b32_e32 v244, v245
	v_mov_b32_e32 v246, v244
	v_mov_b32_e32 v247, v245
	s_nop 1
	v_permlane32_swap_b32_e32 v244, v246
	v_permlane32_swap_b32_e32 v245, v247
	v_mov_b32_e32 v172, v244
	v_mov_b32_e32 v173, v245
	v_mov_b32_e32 v174, v246
	s_waitcnt lgkmcnt(2)
	v_cndmask_b32_e64 v172, v172, 0, s[10:11]
	s_waitcnt lgkmcnt(1)
	v_cndmask_b32_e64 v173, 0, v173, s[12:13]
	v_add_f32_e32 v172, v172, v173
	s_waitcnt lgkmcnt(0)
	v_cndmask_b32_e64 v173, 0, v174, s[6:7]
	v_add_f32_e32 v172, v172, v173
	v_add_f32_e32 v164, v164, v172
	v_add_f32_e32 v165, v165, v172
	ds_write2st64_b32 v141, v164, v165 offset0:24 offset1:26
	v_add_f32_e32 v164, v166, v172
	v_add_f32_e32 v107, v107, v172
	ds_write2st64_b32 v141, v164, v107 offset0:28 offset1:30
	v_add_f32_e32 v107, v167, v172
	v_add_f32_e32 v164, v168, v172
	ds_write2st64_b32 v141, v107, v164 offset0:32 offset1:34
	v_add_f32_e32 v107, v169, v172
	v_add_f32_e32 v164, v170, v172
	ds_write2st64_b32 v141, v107, v164 offset0:36 offset1:38
	v_add_f32_e32 v107, v171, v172
	v_add_f32_e32 v1, v1, v172
	ds_write2st64_b32 v141, v107, v1 offset0:40 offset1:42
	v_add_f32_e32 v1, v172, v108
	v_add_f32_e32 v107, v172, v109
	ds_write2st64_b32 v141, v1, v107 offset0:44 offset1:46
	v_add_f32_e32 v1, v172, v160
	v_add_f32_e32 v107, v172, v161
	ds_write2st64_b32 v141, v1, v107 offset0:48 offset1:50
	v_add_f32_e32 v1, v172, v162
	v_add_f32_e32 v107, v172, v163
	ds_write2st64_b32 v141, v1, v107 offset0:52 offset1:54
	s_waitcnt lgkmcnt(0)
	s_barrier
	s_and_saveexec_b64 s[50:51], s[4:5]
	s_cbranch_execz .LBB0_504
	ds_read_b32 v1, v127 offset:38400
	v_lshl_add_u32 v107, s79, 9, v127
	s_waitcnt lgkmcnt(0)
	v_mul_f32_e32 v255, 0x3fb8aa3b, v1
	v_exp_f32_e32 v255, v255
	s_nop 0
	ds_write_b32 v107, v255 offset:4096

.LBB0_580:
	s_add_u32 s0, s50, s38
	s_addc_u32 s1, s51, s39
	s_add_u32 s60, s48, s38
	s_addc_u32 s61, s49, s39
	s_add_u32 s31, s60, s46
	s_addc_u32 s44, s61, 0
	s_add_u32 s62, s31, 0x16e40800
	s_addc_u32 s63, s44, 0
	s_and_b32 s59, s58, 1
	s_cmp_eq_u32 s59, 0
	s_cselect_b64 s[44:45], -1, 0
	s_and_b64 s[64:65], s[44:45], exec
	s_cselect_b32 s31, 0xf0, s54
	v_and_b32_e32 v136, 63, v154
	v_lshl_add_u32 v136, v136, 2, s31
	ds_read2st64_b32 v[72:73], v136 offset1:1
	v_lshl_add_u64 v[74:75], s[0:1], 0, v[102:103]
	ds_read2st64_b32 v[80:81], v136 offset0:4 offset1:5
	global_load_dwordx4 v[92:95], v[74:75], off
	global_load_dwordx4 v[96:99], v[74:75], off offset:1024
	ds_read2st64_b32 v[132:133], v136 offset0:2 offset1:3
	v_lshl_add_u64 v[82:83], s[62:63], 0, v[104:105]
	s_waitcnt lgkmcnt(2)
	v_mfma_f32_16x16x4_f32 v[68:71], v72, v155, 0
	v_add_co_u32_e64 v72, s[0:1], s52, v74
	v_mfma_f32_16x16x4_f32 v[68:71], v73, v164, v[68:71]
	s_nop 0
	v_addc_co_u32_e64 v73, s[0:1], 0, v75, s[0:1]
	global_load_dwordx4 v[84:87], v[72:73], off
	global_load_dwordx4 v[88:91], v[72:73], off offset:1024
	v_add_co_u32_e64 v72, s[0:1], s47, v82
	s_nop 1
	v_addc_co_u32_e64 v73, s[0:1], 0, v83, s[0:1]
	s_waitcnt lgkmcnt(0)
	v_mfma_f32_16x16x4_f32 v[124:127], v132, v165, v[68:71]
	v_add_co_u32_e64 v134, s[0:1], s52, v82
	global_load_dwordx4 v[68:71], v[82:83], off
	s_nop 0
	global_load_dwordx4 v[72:75], v[72:73], off
	v_addc_co_u32_e64 v135, s[0:1], 0, v83, s[0:1]
	v_mfma_f32_16x16x4_f32 v[76:79], v80, v155, 0
	v_add_co_u32_e64 v80, s[0:1], s53, v82
	v_mfma_f32_16x16x4_f32 v[124:127], v133, v166, v[124:127]
	v_mfma_f32_16x16x4_f32 v[128:131], v81, v164, v[76:79]
	v_addc_co_u32_e64 v81, s[0:1], 0, v83, s[0:1]
	s_nop 5
	global_load_dwordx4 v[76:79], v[134:135], off
	s_nop 0
	global_load_dwordx4 v[80:83], v[80:81], off
	ds_read2st64_b32 v[134:135], v136 offset0:6 offset1:7
	v_add_f32_e32 v124, v167, v124
	v_min_f32_e32 v137, 0, v124
	v_mul_f32_e64 v124, |v124|, s55
	v_exp_f32_e32 v124, v124
	v_add_f32_e32 v126, v167, v126
	v_mul_f32_e64 v133, |v126|, s55
	v_exp_f32_e32 v133, v133
	v_add_f32_e32 v124, 1.0, v124
	v_log_f32_e32 v124, v124
	s_waitcnt lgkmcnt(0)
	v_mfma_f32_16x16x4_f32 v[128:131], v134, v165, v[128:131]
	v_add_f32_e32 v133, 1.0, v133
	v_min_f32_e32 v139, 0, v126
	v_fmac_f32_e32 v137, 0xbf317218, v124
	v_log_f32_e32 v124, v133
	v_add_f32_e32 v134, v167, v127
	v_add_f32_e32 v125, v167, v125
	v_mul_f32_e64 v132, |v125|, s55
	v_fmac_f32_e32 v139, 0xbf317218, v124
	v_mul_f32_e64 v124, |v134|, s55
	v_min_f32_e32 v138, 0, v125
	v_exp_f32_e32 v140, v124
	v_mfma_f32_16x16x4_f32 v[124:127], v135, v166, v[128:131]
	v_exp_f32_e32 v132, v132
	v_add_f32_e32 v129, 1.0, v140
	v_log_f32_e32 v129, v129
	v_add_f32_e32 v132, 1.0, v132
	v_log_f32_e32 v132, v132
	v_min_f32_e32 v140, 0, v134
	s_nop 3
	v_add_f32_e32 v124, v167, v124
	v_mul_f32_e64 v128, |v124|, s55
	v_fmac_f32_e32 v138, 0xbf317218, v132
	v_exp_f32_e32 v128, v128
	ds_read2st64_b32 v[132:133], v136 offset0:8 offset1:9
	v_min_f32_e32 v141, 0, v124
	v_fmac_f32_e32 v140, 0xbf317218, v129
	v_add_f32_e32 v128, 1.0, v128
	v_log_f32_e32 v128, v128
	ds_read2st64_b32 v[134:135], v136 offset0:10 offset1:11
	v_add_f32_e32 v124, v167, v125
	v_mul_f32_e64 v125, |v124|, s55
	v_fmac_f32_e32 v141, 0xbf317218, v128
	s_waitcnt lgkmcnt(1)
	v_mfma_f32_16x16x4_f32 v[128:131], v132, v155, 0
	v_add_f32_e32 v132, v167, v126
	v_exp_f32_e32 v125, v125
	v_mul_f32_e64 v126, |v132|, s55
	v_exp_f32_e32 v126, v126
	v_min_f32_e32 v142, 0, v124
	v_add_f32_e32 v124, 1.0, v125
	v_add_f32_e32 v144, v167, v127
	v_mfma_f32_16x16x4_f32 v[128:131], v133, v164, v[128:131]
	v_log_f32_e32 v133, v124
	v_add_f32_e32 v124, 1.0, v126
	v_log_f32_e32 v143, v124
	v_mul_f32_e64 v145, |v144|, s55
	v_fmac_f32_e32 v142, 0xbf317218, v133
	s_waitcnt lgkmcnt(0)
	v_mfma_f32_16x16x4_f32 v[124:127], v134, v165, v[128:131]
	s_nop 2
	v_exp_f32_e32 v128, v145
	v_min_f32_e32 v145, 0, v132
	ds_read2st64_b32 v[132:133], v136 offset0:12 offset1:13
	v_fmac_f32_e32 v145, 0xbf317218, v143
	v_add_f32_e32 v128, 1.0, v128
	v_log_f32_e32 v128, v128
	v_min_f32_e32 v143, 0, v144
	v_mfma_f32_16x16x4_f32 v[124:127], v135, v166, v[124:127]
	v_fmac_f32_e32 v143, 0xbf317218, v128
	s_nop 8
	v_add_f32_e32 v124, v167, v124
	v_mul_f32_e64 v128, |v124|, s55
	v_exp_f32_e32 v134, v128
	s_waitcnt lgkmcnt(0)
	v_mfma_f32_16x16x4_f32 v[128:131], v132, v155, 0
	v_add_f32_e32 v125, v167, v125
	v_mul_f32_e64 v135, |v125|, s55
	v_exp_f32_e32 v132, v135
	v_min_f32_e32 v144, 0, v124
	v_add_f32_e32 v124, 1.0, v134
	ds_read2st64_b32 v[134:135], v136 offset0:14 offset1:15
	v_add_f32_e32 v132, 1.0, v132
	v_mfma_f32_16x16x4_f32 v[128:131], v133, v164, v[128:131]
	v_log_f32_e32 v132, v132
	v_log_f32_e32 v124, v124
	v_min_f32_e32 v133, 0, v125
	v_add_f32_e32 v146, v167, v127
	v_fmac_f32_e32 v133, 0xbf317218, v132
	v_add_f32_e32 v132, v167, v126
	v_fmac_f32_e32 v144, 0xbf317218, v124
	v_mul_f32_e64 v124, |v132|, s55
	v_exp_f32_e32 v136, v124
	s_waitcnt lgkmcnt(0)
	v_mfma_f32_16x16x4_f32 v[124:127], v134, v165, v[128:131]
	v_mul_f32_e64 v128, |v146|, s55
	v_exp_f32_e32 v128, v128
	v_add_f32_e32 v130, 1.0, v136
	v_log_f32_e32 v130, v130
	v_min_f32_e32 v129, 0, v132
	v_add_f32_e32 v128, 1.0, v128
	v_log_f32_e32 v128, v128
	v_mfma_f32_16x16x4_f32 v[124:127], v135, v166, v[124:127]
	v_fmac_f32_e32 v129, 0xbf317218, v130
	v_min_f32_e32 v130, 0, v146
	v_fmac_f32_e32 v130, 0xbf317218, v128
	s_nop 6
	v_add_f32_e32 v124, v167, v124
	v_mul_f32_e64 v131, |v124|, s55
	v_exp_f32_e32 v131, v131
	v_add_f32_e32 v125, v167, v125
	v_min_f32_e32 v124, 0, v124
	v_add_f32_e32 v126, v167, v126
	v_add_f32_e32 v128, 1.0, v131
	v_mul_f32_e64 v131, |v125|, s55
	v_log_f32_e32 v128, v128
	v_exp_f32_e32 v131, v131
	v_add_f32_e32 v127, v167, v127
	v_mul_f32_e64 v132, |v127|, s55
	v_fmac_f32_e32 v124, 0xbf317218, v128
	v_add_f32_e32 v128, 1.0, v131
	v_mul_f32_e64 v131, |v126|, s55
	v_log_f32_e32 v128, v128
	v_exp_f32_e32 v131, v131
	v_exp_f32_e32 v132, v132
	v_min_f32_e32 v125, 0, v125
	v_fmac_f32_e32 v125, 0xbf317218, v128
	v_add_f32_e32 v128, 1.0, v131
	v_add_f32_e32 v131, 1.0, v132
	v_log_f32_e32 v131, v131
	v_log_f32_e32 v128, v128
	v_min_f32_e32 v127, 0, v127
	v_min_f32_e32 v126, 0, v126
	v_fmac_f32_e32 v127, 0xbf317218, v131
	v_fmac_f32_e32 v126, 0xbf317218, v128
	v_fma_f32 v127, v127, s56, 0
	v_fmamk_f32 v126, v126, 0x3d800000, v127
	v_fmamk_f32 v125, v125, 0x3d800000, v126
	v_fmamk_f32 v124, v124, 0x3d800000, v125
	v_fmamk_f32 v128, v130, 0x3d800000, v124
	v_fmamk_f32 v129, v129, 0x3d800000, v128
	v_fmamk_f32 v130, v133, 0x3d800000, v129
	v_fmamk_f32 v131, v144, 0x3d800000, v130
	v_fmamk_f32 v132, v143, 0x3d800000, v131
	v_fmamk_f32 v133, v145, 0x3d800000, v132
	v_fmamk_f32 v134, v142, 0x3d800000, v133
	v_fmamk_f32 v135, v141, 0x3d800000, v134
	v_fmamk_f32 v136, v140, 0x3d800000, v135
	v_fmamk_f32 v139, v139, 0x3d800000, v136
	v_fmamk_f32 v138, v138, 0x3d800000, v139
	v_fmamk_f32 v137, v137, 0x3d800000, v138
	v_mov_b32_e32 v244, v137
	v_mov_b32_e32 v245, v137
	s_nop 1
	v_permlane16_swap_b32_e32 v244, v245
	v_mov_b32_e32 v246, v244
	v_mov_b32_e32 v247, v245
	s_nop 1
	v_permlane32_swap_b32_e32 v244, v246
	v_permlane32_swap_b32_e32 v245, v247
	v_mov_b32_e32 v140, v247
	v_mov_b32_e32 v141, v246
	v_mov_b32_e32 v142, v245
	s_waitcnt lgkmcnt(2)
	v_cndmask_b32_e64 v140, v140, 0, s[2:3]
	s_waitcnt lgkmcnt(1)
	v_cndmask_b32_e64 v141, 0, v141, s[4:5]
	v_add_f32_e32 v140, v141, v140
	s_waitcnt lgkmcnt(0)
	v_cndmask_b32_e64 v141, 0, v142, s[6:7]
	v_add_f32_e32 v140, v141, v140
	v_add_f32_e32 v137, v140, v137
	v_add_f32_e32 v138, v140, v138
	v_add_f32_e32 v124, v140, v124
	v_add_f32_e32 v125, v140, v125
	ds_write2st64_b32 v184, v137, v138 offset0:24 offset1:26
	v_add_f32_e32 v137, v140, v139
	v_add_f32_e32 v136, v140, v136
	v_add_f32_e32 v135, v140, v135
	v_add_f32_e32 v134, v140, v134
	v_add_f32_e32 v133, v140, v133
	v_add_f32_e32 v132, v140, v132
	v_add_f32_e32 v131, v140, v131
	v_add_f32_e32 v130, v140, v130
	v_add_f32_e32 v129, v140, v129
	v_add_f32_e32 v128, v140, v128
	ds_write2st64_b32 v184, v124, v125 offset0:48 offset1:50
	v_add_f32_e32 v124, v140, v126
	v_add_f32_e32 v125, v140, v127
	ds_write2st64_b32 v184, v137, v136 offset0:28 offset1:30
	ds_write2st64_b32 v184, v135, v134 offset0:32 offset1:34
	ds_write2st64_b32 v184, v133, v132 offset0:36 offset1:38
	ds_write2st64_b32 v184, v131, v130 offset0:40 offset1:42
	ds_write2st64_b32 v184, v129, v128 offset0:44 offset1:46
	ds_write2st64_b32 v184, v124, v125 offset0:52 offset1:54
	s_waitcnt lgkmcnt(0)
	s_barrier
	s_and_saveexec_b64 s[0:1], s[8:9]
	s_cbranch_execz .LBB0_582
	ds_read_b32 v124, v175 offset:6144
	v_lshl_add_u32 v125, s59, 9, v175
	s_waitcnt lgkmcnt(0)
	v_mul_f32_e32 v255, 0x3fb8aa3b, v124
	v_exp_f32_e32 v255, v255
	s_nop 0
	ds_write_b32 v125, v255 offset:4096

.LBB0_664:
	s_add_u32 s62, s61, s76
	s_addc_u32 s63, s91, s77
	v_lshl_add_u64 v[70:71], s[62:63], 0, v[112:113]
	s_add_u32 s62, s55, s76
	s_addc_u32 s63, s57, s77
	s_add_u32 s62, s62, s68
	v_add_co_u32_e32 v74, vcc, s95, v70
	s_addc_u32 s63, s63, 0
	s_nop 0
	v_addc_co_u32_e32 v75, vcc, 0, v71, vcc
	v_lshl_add_u64 v[86:87], s[62:63], 0, v[114:115]
	v_add_co_u32_e32 v78, vcc, s81, v86
	s_and_b32 s93, s92, 1
	s_add_i32 s69, s66, 0xf0
	v_addc_co_u32_e32 v79, vcc, 0, v87, vcc
	s_cmp_eq_u32 s93, 0
	v_add_co_u32_e32 v82, vcc, s95, v86
	s_cselect_b64 s[78:79], -1, 0
	s_nop 0
	v_addc_co_u32_e32 v83, vcc, 0, v87, vcc
	s_and_b64 s[62:63], s[78:79], exec
	global_load_dwordx4 v[94:97], v[70:71], off
	global_load_dwordx4 v[98:101], v[70:71], off offset:1024
	s_nop 0
	global_load_dwordx4 v[70:73], v[74:75], off
	global_load_dwordx4 v[90:93], v[74:75], off offset:1024
	s_cselect_b32 s62, 0xf0, s69
	global_load_dwordx4 v[74:77], v[86:87], off
	v_add_co_u32_e32 v86, vcc, s96, v86
	v_and_b32_e32 v137, 63, v154
	v_lshl_add_u32 v137, v137, 2, s62
	s_nop 0
	v_addc_co_u32_e32 v87, vcc, 0, v87, vcc
	global_load_dwordx4 v[78:81], v[78:79], off
	s_nop 0
	global_load_dwordx4 v[82:85], v[82:83], off
	s_nop 0
	global_load_dwordx4 v[86:89], v[86:87], off
	ds_read2st64_b32 v[134:135], v137 offset1:1
	ds_read2st64_b32 v[142:143], v137 offset0:2 offset1:3
	s_waitcnt lgkmcnt(1)
	v_mfma_f32_16x16x4_f32 v[138:141], v134, v104, 0
	ds_read2st64_b32 v[146:147], v137 offset0:8 offset1:9
	v_mfma_f32_16x16x4_f32 v[138:141], v135, v105, v[138:141]
	s_waitcnt lgkmcnt(1)
	v_mfma_f32_16x16x4_f32 v[138:141], v142, v106, v[138:141]
	v_mfma_f32_16x16x4_f32 v[138:141], v143, v107, v[138:141]
	ds_read2st64_b32 v[142:143], v137 offset0:4 offset1:5
	s_nop 8
	v_add_f32_e32 v134, v108, v138
	v_min_f32_e32 v109, 0, v134
	v_mul_f32_e64 v134, |v134|, s97
	v_exp_f32_e32 v134, v134
	v_add_f32_e32 v135, v108, v139
	v_add_f32_e32 v136, v108, v140
	v_add_f32_e32 v138, v108, v141
	v_add_f32_e32 v134, 1.0, v134
	v_log_f32_e32 v134, v134
	s_nop 0
	v_fmac_f32_e32 v109, 0xbf317218, v134
	v_min_f32_e32 v134, 0, v135
	v_mul_f32_e64 v135, |v135|, s97
	v_exp_f32_e32 v135, v135
	v_fma_f32 v109, v109, s0, 0
	v_add_f32_e32 v135, 1.0, v135
	v_log_f32_e32 v135, v135
	s_nop 0
	v_fmac_f32_e32 v134, 0xbf317218, v135
	v_min_f32_e32 v135, 0, v136
	v_mul_f32_e64 v136, |v136|, s97
	v_exp_f32_e32 v136, v136
	v_fmamk_f32 v134, v134, 0x3d800000, v109
	v_add_f32_e32 v136, 1.0, v136
	v_log_f32_e32 v136, v136
	s_nop 0
	v_fmac_f32_e32 v135, 0xbf317218, v136
	v_min_f32_e32 v136, 0, v138
	v_mul_f32_e64 v138, |v138|, s97
	v_exp_f32_e32 v138, v138
	v_fmamk_f32 v135, v135, 0x3d800000, v134
	v_add_f32_e32 v138, 1.0, v138
	v_log_f32_e32 v138, v138
	s_nop 0
	v_fmac_f32_e32 v136, 0xbf317218, v138
	s_waitcnt lgkmcnt(0)
	v_mfma_f32_16x16x4_f32 v[138:141], v142, v104, 0
	v_fmamk_f32 v136, v136, 0x3d800000, v135
	v_mfma_f32_16x16x4_f32 v[138:141], v143, v105, v[138:141]
	ds_read2st64_b32 v[142:143], v137 offset0:6 offset1:7
	s_waitcnt lgkmcnt(0)
	v_mfma_f32_16x16x4_f32 v[138:141], v142, v106, v[138:141]
	v_mfma_f32_16x16x4_f32 v[138:141], v143, v107, v[138:141]
	s_nop 9
	v_add_f32_e32 v142, v108, v138
	v_min_f32_e32 v138, 0, v142
	v_mul_f32_e64 v142, |v142|, s97
	v_exp_f32_e32 v142, v142
	s_nop 0
	v_add_f32_e32 v142, 1.0, v142
	v_log_f32_e32 v142, v142
	s_nop 0
	v_fmac_f32_e32 v138, 0xbf317218, v142
	v_add_f32_e32 v142, v108, v139
	v_min_f32_e32 v139, 0, v142
	v_mul_f32_e64 v142, |v142|, s97
	v_exp_f32_e32 v142, v142
	s_nop 0
	v_add_f32_e32 v142, 1.0, v142
	v_log_f32_e32 v142, v142
	s_nop 0
	v_fmac_f32_e32 v139, 0xbf317218, v142
	v_add_f32_e32 v142, v108, v140
	v_min_f32_e32 v140, 0, v142
	v_mul_f32_e64 v142, |v142|, s97
	v_exp_f32_e32 v142, v142
	s_nop 0
	v_add_f32_e32 v142, 1.0, v142
	v_log_f32_e32 v142, v142
	s_nop 0
	v_fmac_f32_e32 v140, 0xbf317218, v142
	v_add_f32_e32 v142, v108, v141
	v_min_f32_e32 v141, 0, v142
	v_mul_f32_e64 v142, |v142|, s97
	v_exp_f32_e32 v142, v142
	s_nop 0
	v_add_f32_e32 v142, 1.0, v142
	v_log_f32_e32 v142, v142
	s_nop 0
	v_fmac_f32_e32 v141, 0xbf317218, v142
	v_mfma_f32_16x16x4_f32 v[142:145], v146, v104, 0
	v_mfma_f32_16x16x4_f32 v[142:145], v147, v105, v[142:145]
	ds_read2st64_b32 v[146:147], v137 offset0:10 offset1:11
	s_waitcnt lgkmcnt(0)
	v_mfma_f32_16x16x4_f32 v[142:145], v146, v106, v[142:145]
	v_mfma_f32_16x16x4_f32 v[142:145], v147, v107, v[142:145]
	ds_read2st64_b32 v[146:147], v137 offset0:12 offset1:13
	s_nop 8
	v_add_f32_e32 v142, v108, v142
	v_min_f32_e32 v148, 0, v142
	v_mul_f32_e64 v142, |v142|, s97
	v_exp_f32_e32 v142, v142
	s_nop 0
	v_add_f32_e32 v142, 1.0, v142
	v_log_f32_e32 v142, v142
	s_nop 0
	v_fmac_f32_e32 v148, 0xbf317218, v142
	v_add_f32_e32 v142, v108, v143
	v_min_f32_e32 v149, 0, v142
	v_mul_f32_e64 v142, |v142|, s97
	v_exp_f32_e32 v142, v142
	s_nop 0
	v_add_f32_e32 v142, 1.0, v142
	v_log_f32_e32 v142, v142
	s_nop 0
	v_fmac_f32_e32 v149, 0xbf317218, v142
	v_add_f32_e32 v142, v108, v144
	v_min_f32_e32 v150, 0, v142
	v_mul_f32_e64 v142, |v142|, s97
	v_exp_f32_e32 v142, v142
	s_nop 0
	v_add_f32_e32 v142, 1.0, v142
	v_log_f32_e32 v142, v142
	s_nop 0
	v_fmac_f32_e32 v150, 0xbf317218, v142
	v_add_f32_e32 v142, v108, v145
	v_min_f32_e32 v151, 0, v142
	v_mul_f32_e64 v142, |v142|, s97
	v_exp_f32_e32 v142, v142
	s_nop 0
	v_add_f32_e32 v142, 1.0, v142
	v_log_f32_e32 v142, v142
	s_nop 0
	v_fmac_f32_e32 v151, 0xbf317218, v142
	s_waitcnt lgkmcnt(0)
	v_mfma_f32_16x16x4_f32 v[142:145], v146, v104, 0
	v_mfma_f32_16x16x4_f32 v[142:145], v147, v105, v[142:145]
	ds_read2st64_b32 v[146:147], v137 offset0:14 offset1:15
	s_waitcnt lgkmcnt(0)
	v_mfma_f32_16x16x4_f32 v[142:145], v146, v106, v[142:145]
	v_mfma_f32_16x16x4_f32 v[142:145], v147, v107, v[142:145]
	s_nop 9
	v_add_f32_e32 v137, v108, v142
	v_min_f32_e32 v142, 0, v137
	v_mul_f32_e64 v137, |v137|, s97
	v_exp_f32_e32 v137, v137
	s_nop 0
	v_add_f32_e32 v137, 1.0, v137
	v_log_f32_e32 v137, v137
	s_nop 0
	v_fmac_f32_e32 v142, 0xbf317218, v137
	v_add_f32_e32 v137, v108, v143
	v_min_f32_e32 v143, 0, v137
	v_mul_f32_e64 v137, |v137|, s97
	v_exp_f32_e32 v137, v137
	s_nop 0
	v_add_f32_e32 v137, 1.0, v137
	v_log_f32_e32 v137, v137
	s_nop 0
	v_fmac_f32_e32 v143, 0xbf317218, v137
	v_add_f32_e32 v137, v108, v144
	v_min_f32_e32 v144, 0, v137
	v_mul_f32_e64 v137, |v137|, s97
	v_exp_f32_e32 v137, v137
	s_nop 0
	v_add_f32_e32 v137, 1.0, v137
	v_log_f32_e32 v137, v137
	s_nop 0
	v_fmac_f32_e32 v144, 0xbf317218, v137
	v_add_f32_e32 v137, v108, v145
	v_min_f32_e32 v145, 0, v137
	v_mul_f32_e64 v137, |v137|, s97
	v_exp_f32_e32 v137, v137
	s_nop 0
	v_add_f32_e32 v137, 1.0, v137
	v_log_f32_e32 v137, v137
	s_nop 0
	v_fmac_f32_e32 v145, 0xbf317218, v137
	v_fmamk_f32 v137, v138, 0x3d800000, v136
	v_fmamk_f32 v138, v139, 0x3d800000, v137
	v_fmamk_f32 v139, v140, 0x3d800000, v138
	v_fmamk_f32 v140, v141, 0x3d800000, v139
	v_fmamk_f32 v141, v148, 0x3d800000, v140
	v_fmamk_f32 v146, v149, 0x3d800000, v141
	v_fmamk_f32 v147, v150, 0x3d800000, v146
	v_fmamk_f32 v148, v151, 0x3d800000, v147
	v_fmamk_f32 v142, v142, 0x3d800000, v148
	v_fmamk_f32 v143, v143, 0x3d800000, v142
	v_fmamk_f32 v144, v144, 0x3d800000, v143
	v_fmamk_f32 v145, v145, 0x3d800000, v144
	v_mov_b32_e32 v244, v145
	v_mov_b32_e32 v245, v145
	s_nop 1
	v_permlane16_swap_b32_e32 v244, v245
	v_mov_b32_e32 v246, v244
	v_mov_b32_e32 v247, v245
	s_nop 1
	v_permlane32_swap_b32_e32 v244, v246
	v_permlane32_swap_b32_e32 v245, v247
	v_mov_b32_e32 v149, v244
	v_mov_b32_e32 v150, v245
	v_mov_b32_e32 v151, v246
	s_waitcnt lgkmcnt(2)
	v_cndmask_b32_e64 v149, v149, 0, s[4:5]
	s_waitcnt lgkmcnt(1)
	v_cndmask_b32_e64 v150, 0, v150, s[6:7]
	v_add_f32_e32 v149, v149, v150
	s_waitcnt lgkmcnt(0)
	v_cndmask_b32_e64 v150, 0, v151, s[8:9]
	v_add_f32_e32 v149, v149, v150
	v_add_f32_e32 v109, v109, v149
	v_add_f32_e32 v134, v134, v149
	ds_write2st64_b32 v200, v109, v134 offset0:24 offset1:26
	v_add_f32_e32 v109, v135, v149
	v_add_f32_e32 v134, v136, v149
	ds_write2st64_b32 v200, v109, v134 offset0:28 offset1:30
	v_add_f32_e32 v109, v137, v149
	v_add_f32_e32 v134, v138, v149
	ds_write2st64_b32 v200, v109, v134 offset0:32 offset1:34
	v_add_f32_e32 v109, v139, v149
	v_add_f32_e32 v134, v140, v149
	ds_write2st64_b32 v200, v109, v134 offset0:36 offset1:38
	v_add_f32_e32 v109, v141, v149
	v_add_f32_e32 v134, v146, v149
	ds_write2st64_b32 v200, v109, v134 offset0:40 offset1:42
	v_add_f32_e32 v109, v149, v147
	v_add_f32_e32 v134, v149, v148
	ds_write2st64_b32 v200, v109, v134 offset0:44 offset1:46
	v_add_f32_e32 v109, v149, v142
	v_add_f32_e32 v134, v149, v143
	ds_write2st64_b32 v200, v109, v134 offset0:48 offset1:50
	v_add_f32_e32 v109, v149, v144
	v_add_f32_e32 v134, v149, v145
	ds_write2st64_b32 v200, v109, v134 offset0:52 offset1:54
	s_waitcnt lgkmcnt(0)
	s_barrier
	s_and_saveexec_b64 s[62:63], s[10:11]
	s_cbranch_execz .LBB0_666
	ds_read_b32 v109, v178 offset:38400
	v_lshl_add_u32 v134, s93, 9, v178
	s_waitcnt lgkmcnt(0)
	v_mul_f32_e32 v255, 0x3fb8aa3b, v109
	v_exp_f32_e32 v255, v255
	s_nop 0
	ds_write_b32 v134, v255 offset:4096

.LBB0_680:
	s_add_u32 s62, s71, s60
	s_addc_u32 s63, s74, s61
	s_add_u32 s72, s48, s60
	s_addc_u32 s73, s70, s61
	s_add_u32 s55, s72, s68
	v_lshl_add_u64 v[70:71], s[62:63], 0, v[112:113]
	s_addc_u32 s63, s73, 0
	s_add_u32 s62, s55, 0xafc0800
	v_add_co_u32_e32 v74, vcc, s95, v70
	s_addc_u32 s63, s63, 0
	s_nop 0
	v_addc_co_u32_e32 v75, vcc, 0, v71, vcc
	v_lshl_add_u64 v[86:87], s[62:63], 0, v[114:115]
	v_add_co_u32_e32 v78, vcc, s81, v86
	s_and_b32 s67, s75, 1
	s_nop 0
	v_addc_co_u32_e32 v79, vcc, 0, v87, vcc
	s_cmp_eq_u32 s67, 0
	v_add_co_u32_e32 v82, vcc, s95, v86
	s_cselect_b64 s[64:65], -1, 0
	s_nop 0
	v_addc_co_u32_e32 v83, vcc, 0, v87, vcc
	s_and_b64 s[62:63], s[64:65], exec
	global_load_dwordx4 v[94:97], v[70:71], off
	global_load_dwordx4 v[98:101], v[70:71], off offset:1024
	s_nop 0
	global_load_dwordx4 v[70:73], v[74:75], off
	global_load_dwordx4 v[90:93], v[74:75], off offset:1024
	s_cselect_b32 s55, 0xf0, s69
	global_load_dwordx4 v[74:77], v[86:87], off
	v_add_co_u32_e32 v86, vcc, s96, v86
	v_and_b32_e32 v105, 63, v154
	v_lshl_add_u32 v105, v105, 2, s55
	s_nop 0
	v_addc_co_u32_e32 v87, vcc, 0, v87, vcc
	global_load_dwordx4 v[78:81], v[78:79], off
	s_nop 0
	global_load_dwordx4 v[82:85], v[82:83], off
	s_nop 0
	global_load_dwordx4 v[86:89], v[86:87], off
	ds_read2st64_b32 v[102:103], v105 offset1:1
	ds_read2st64_b32 v[136:137], v105 offset0:2 offset1:3
	s_waitcnt vmcnt(12) lgkmcnt(1)
	v_mfma_f32_16x16x4_f32 v[106:109], v102, v219, 0
	ds_read2st64_b32 v[140:141], v105 offset0:8 offset1:9
	s_waitcnt vmcnt(11)
	v_mfma_f32_16x16x4_f32 v[106:109], v103, v220, v[106:109]
	s_waitcnt vmcnt(10) lgkmcnt(1)
	v_mfma_f32_16x16x4_f32 v[106:109], v136, v221, v[106:109]
	s_waitcnt vmcnt(9)
	v_mfma_f32_16x16x4_f32 v[106:109], v137, v222, v[106:109]
	ds_read2st64_b32 v[136:137], v105 offset0:4 offset1:5
	s_waitcnt vmcnt(8)
	s_nop 7
	v_add_f32_e32 v102, v223, v106
	v_min_f32_e32 v0, 0, v102
	v_mul_f32_e64 v102, |v102|, s97
	v_exp_f32_e32 v102, v102
	v_add_f32_e32 v103, v223, v107
	v_add_f32_e32 v104, v223, v108
	v_add_f32_e32 v106, v223, v109
	v_add_f32_e32 v102, 1.0, v102
	v_log_f32_e32 v102, v102
	s_nop 0
	v_fmac_f32_e32 v0, 0xbf317218, v102
	v_min_f32_e32 v102, 0, v103
	v_mul_f32_e64 v103, |v103|, s97
	v_exp_f32_e32 v103, v103
	s_nop 0
	v_add_f32_e32 v103, 1.0, v103
	v_log_f32_e32 v103, v103
	s_nop 0
	v_fmac_f32_e32 v102, 0xbf317218, v103
	v_min_f32_e32 v103, 0, v104
	v_mul_f32_e64 v104, |v104|, s97
	v_exp_f32_e32 v104, v104
	s_nop 0
	v_add_f32_e32 v104, 1.0, v104
	v_log_f32_e32 v104, v104
	s_nop 0
	v_fmac_f32_e32 v103, 0xbf317218, v104
	v_min_f32_e32 v104, 0, v106
	v_mul_f32_e64 v106, |v106|, s97
	v_exp_f32_e32 v106, v106
	s_nop 0
	v_add_f32_e32 v106, 1.0, v106
	v_log_f32_e32 v106, v106
	s_nop 0
	v_fmac_f32_e32 v104, 0xbf317218, v106
	s_waitcnt lgkmcnt(0)
	v_mfma_f32_16x16x4_f32 v[106:109], v136, v219, 0
	v_mfma_f32_16x16x4_f32 v[106:109], v137, v220, v[106:109]
	ds_read2st64_b32 v[136:137], v105 offset0:6 offset1:7
	s_waitcnt lgkmcnt(0)
	v_mfma_f32_16x16x4_f32 v[106:109], v136, v221, v[106:109]
	v_mfma_f32_16x16x4_f32 v[106:109], v137, v222, v[106:109]
	s_nop 9
	v_add_f32_e32 v136, v223, v106
	v_min_f32_e32 v106, 0, v136
	v_mul_f32_e64 v136, |v136|, s97
	v_exp_f32_e32 v136, v136
	s_nop 0
	v_add_f32_e32 v136, 1.0, v136
	v_log_f32_e32 v136, v136
	s_nop 0
	v_fmac_f32_e32 v106, 0xbf317218, v136
	v_add_f32_e32 v136, v223, v107
	v_min_f32_e32 v107, 0, v136
	v_mul_f32_e64 v136, |v136|, s97
	v_exp_f32_e32 v136, v136
	s_nop 0
	v_add_f32_e32 v136, 1.0, v136
	v_log_f32_e32 v136, v136
	s_nop 0
	v_fmac_f32_e32 v107, 0xbf317218, v136
	v_add_f32_e32 v136, v223, v108
	v_min_f32_e32 v108, 0, v136
	v_mul_f32_e64 v136, |v136|, s97
	v_exp_f32_e32 v136, v136
	s_nop 0
	v_add_f32_e32 v136, 1.0, v136
	v_log_f32_e32 v136, v136
	s_nop 0
	v_fmac_f32_e32 v108, 0xbf317218, v136
	v_add_f32_e32 v136, v223, v109
	v_min_f32_e32 v109, 0, v136
	v_mul_f32_e64 v136, |v136|, s97
	v_exp_f32_e32 v136, v136
	s_nop 0
	v_add_f32_e32 v136, 1.0, v136
	v_log_f32_e32 v136, v136
	s_nop 0
	v_fmac_f32_e32 v109, 0xbf317218, v136
	v_mfma_f32_16x16x4_f32 v[136:139], v140, v219, 0
	v_mfma_f32_16x16x4_f32 v[136:139], v141, v220, v[136:139]
	ds_read2st64_b32 v[140:141], v105 offset0:10 offset1:11
	s_waitcnt lgkmcnt(0)
	v_mfma_f32_16x16x4_f32 v[136:139], v140, v221, v[136:139]
	v_mfma_f32_16x16x4_f32 v[136:139], v141, v222, v[136:139]
	ds_read2st64_b32 v[140:141], v105 offset0:12 offset1:13
	s_nop 8
	v_add_f32_e32 v136, v223, v136
	v_min_f32_e32 v142, 0, v136
	v_mul_f32_e64 v136, |v136|, s97
	v_exp_f32_e32 v136, v136
	s_nop 0
	v_add_f32_e32 v136, 1.0, v136
	v_log_f32_e32 v136, v136
	s_nop 0
	v_fmac_f32_e32 v142, 0xbf317218, v136
	v_add_f32_e32 v136, v223, v137
	v_min_f32_e32 v143, 0, v136
	v_mul_f32_e64 v136, |v136|, s97
	v_exp_f32_e32 v136, v136
	s_nop 0
	v_add_f32_e32 v136, 1.0, v136
	v_log_f32_e32 v136, v136
	s_nop 0
	v_fmac_f32_e32 v143, 0xbf317218, v136
	v_add_f32_e32 v136, v223, v138
	v_min_f32_e32 v144, 0, v136
	v_mul_f32_e64 v136, |v136|, s97
	v_exp_f32_e32 v136, v136
	s_nop 0
	v_add_f32_e32 v136, 1.0, v136
	v_log_f32_e32 v136, v136
	s_nop 0
	v_fmac_f32_e32 v144, 0xbf317218, v136
	v_add_f32_e32 v136, v223, v139
	v_min_f32_e32 v145, 0, v136
	v_mul_f32_e64 v136, |v136|, s97
	v_exp_f32_e32 v136, v136
	s_nop 0
	v_add_f32_e32 v136, 1.0, v136
	v_log_f32_e32 v136, v136
	s_nop 0
	v_fmac_f32_e32 v145, 0xbf317218, v136
	s_waitcnt lgkmcnt(0)
	v_mfma_f32_16x16x4_f32 v[136:139], v140, v219, 0
	v_mfma_f32_16x16x4_f32 v[136:139], v141, v220, v[136:139]
	ds_read2st64_b32 v[140:141], v105 offset0:14 offset1:15
	s_waitcnt lgkmcnt(0)
	v_mfma_f32_16x16x4_f32 v[136:139], v140, v221, v[136:139]
	v_mfma_f32_16x16x4_f32 v[136:139], v141, v222, v[136:139]
	s_nop 9
	v_add_f32_e32 v105, v223, v136
	v_min_f32_e32 v136, 0, v105
	v_mul_f32_e64 v105, |v105|, s97
	v_exp_f32_e32 v105, v105
	s_nop 0
	v_add_f32_e32 v105, 1.0, v105
	v_log_f32_e32 v105, v105
	s_nop 0
	v_fmac_f32_e32 v136, 0xbf317218, v105
	v_add_f32_e32 v105, v223, v137
	v_min_f32_e32 v137, 0, v105
	v_mul_f32_e64 v105, |v105|, s97
	v_exp_f32_e32 v105, v105
	s_nop 0
	v_add_f32_e32 v105, 1.0, v105
	v_log_f32_e32 v105, v105
	s_nop 0
	v_fmac_f32_e32 v137, 0xbf317218, v105
	v_add_f32_e32 v105, v223, v138
	v_min_f32_e32 v138, 0, v105
	v_mul_f32_e64 v105, |v105|, s97
	v_exp_f32_e32 v105, v105
	s_nop 0
	v_add_f32_e32 v105, 1.0, v105
	v_log_f32_e32 v105, v105
	s_nop 0
	v_fmac_f32_e32 v138, 0xbf317218, v105
	v_add_f32_e32 v105, v223, v139
	v_min_f32_e32 v139, 0, v105
	v_mul_f32_e64 v105, |v105|, s97
	v_exp_f32_e32 v105, v105
	s_nop 0
	v_add_f32_e32 v105, 1.0, v105
	v_log_f32_e32 v105, v105
	s_nop 0
	v_fmac_f32_e32 v139, 0xbf317218, v105
	v_fma_f32 v105, v139, s0, 0
	v_fmamk_f32 v138, v138, 0x3d800000, v105
	v_fmamk_f32 v137, v137, 0x3d800000, v138
	v_fmamk_f32 v136, v136, 0x3d800000, v137
	v_fmamk_f32 v139, v145, 0x3d800000, v136
	v_fmamk_f32 v140, v144, 0x3d800000, v139
	v_fmamk_f32 v141, v143, 0x3d800000, v140
	v_fmamk_f32 v142, v142, 0x3d800000, v141
	v_fmamk_f32 v109, v109, 0x3d800000, v142
	v_fmamk_f32 v108, v108, 0x3d800000, v109
	v_fmamk_f32 v107, v107, 0x3d800000, v108
	v_fmamk_f32 v106, v106, 0x3d800000, v107
	v_fmamk_f32 v104, v104, 0x3d800000, v106
	v_fmamk_f32 v103, v103, 0x3d800000, v104
	v_fmamk_f32 v102, v102, 0x3d800000, v103
	v_fmamk_f32 v0, v0, 0x3d800000, v102
	v_mov_b32_e32 v244, v0
	v_mov_b32_e32 v245, v0
	s_nop 1
	v_permlane16_swap_b32_e32 v244, v245
	v_mov_b32_e32 v246, v244
	v_mov_b32_e32 v247, v245
	s_nop 1
	v_permlane32_swap_b32_e32 v244, v246
	v_permlane32_swap_b32_e32 v245, v247
	v_mov_b32_e32 v144, v246
	v_mov_b32_e32 v145, v247
	v_mov_b32_e32 v143, v245
	s_waitcnt lgkmcnt(2)
	v_cndmask_b32_e64 v144, 0, v144, s[28:29]
	s_waitcnt lgkmcnt(1)
	v_cndmask_b32_e64 v145, v145, 0, s[8:9]
	v_add_f32_e32 v144, v144, v145
	s_waitcnt lgkmcnt(0)
	v_cndmask_b32_e64 v143, 0, v143, s[4:5]
	v_add_f32_e32 v143, v143, v144
	v_add_f32_e32 v0, v143, v0
	v_add_f32_e32 v102, v143, v102
	ds_write2st64_b32 v200, v0, v102 offset0:24 offset1:26
	v_add_f32_e32 v0, v143, v103
	v_add_f32_e32 v102, v143, v104
	ds_write2st64_b32 v200, v0, v102 offset0:28 offset1:30
	v_add_f32_e32 v0, v143, v106
	v_add_f32_e32 v102, v143, v107
	ds_write2st64_b32 v200, v0, v102 offset0:32 offset1:34
	v_add_f32_e32 v0, v143, v108
	v_add_f32_e32 v102, v143, v109
	ds_write2st64_b32 v200, v0, v102 offset0:36 offset1:38
	v_add_f32_e32 v0, v143, v142
	v_add_f32_e32 v102, v143, v141
	ds_write2st64_b32 v200, v0, v102 offset0:40 offset1:42
	v_add_f32_e32 v0, v143, v140
	v_add_f32_e32 v102, v143, v139
	ds_write2st64_b32 v200, v0, v102 offset0:44 offset1:46
	v_add_f32_e32 v0, v143, v136
	v_add_f32_e32 v102, v143, v137
	ds_write2st64_b32 v200, v0, v102 offset0:48 offset1:50
	v_add_f32_e32 v0, v143, v138
	v_add_f32_e32 v102, v143, v105
	ds_write2st64_b32 v200, v0, v102 offset0:52 offset1:54
	s_waitcnt lgkmcnt(0)
	s_barrier
	s_and_saveexec_b64 s[62:63], s[10:11]
	s_cbranch_execz .LBB0_682
	ds_read_b32 v0, v178 offset:6144
	v_lshl_add_u32 v102, s67, 9, v178
	s_waitcnt lgkmcnt(0)
	v_mul_f32_e32 v255, 0x3fb8aa3b, v0
	v_exp_f32_e32 v255, v255
	s_nop 0
	ds_write_b32 v102, v255 offset:4096

.LBB0_2090:
	v_mov_b32_e32 v244, v169
	v_mov_b32_e32 v245, v169
	s_nop 1
	v_permlane16_swap_b32_e32 v244, v245
	v_mov_b32_e32 v246, v244
	v_mov_b32_e32 v247, v245
	s_nop 1
	v_permlane32_swap_b32_e32 v244, v246
	v_permlane32_swap_b32_e32 v245, v247
	v_mov_b32_e32 v138, v244
	v_mov_b32_e32 v139, v245
	v_mov_b32_e32 v137, v246
	v_mov_b32_e32 v140, v247
	s_mov_b64 s[30:31], -1
	s_and_b64 vcc, exec, s[26:27]
	s_cbranch_vccz .LBB0_2092
	s_waitcnt lgkmcnt(0)
	v_cndmask_b32_e64 v136, v140, 0, s[6:7]
	v_cndmask_b32_e64 v140, 0, v137, s[8:9]
	v_add_f32_e32 v136, v140, v136
	v_cndmask_b32_e64 v140, 0, v139, s[10:11]
	v_add_f32_e32 v136, v140, v136
	s_mov_b64 s[30:31], 0

.LBB0_2105:
	v_mov_b32_e32 v244, v159
	v_mov_b32_e32 v245, v159
	s_nop 1
	v_permlane16_swap_b32_e32 v244, v245
	v_mov_b32_e32 v246, v244
	v_mov_b32_e32 v247, v245
	s_nop 1
	v_permlane32_swap_b32_e32 v244, v246
	v_permlane32_swap_b32_e32 v245, v247
	v_mov_b32_e32 v92, v244
	v_mov_b32_e32 v93, v245
	v_mov_b32_e32 v91, v246
	v_mov_b32_e32 v134, v247
	s_and_b64 vcc, exec, s[14:15]
	s_mov_b64 s[14:15], -1
	s_cbranch_vccnz .LBB0_2107
	s_waitcnt lgkmcnt(0)
	v_cndmask_b32_e64 v90, v134, 0, s[6:7]
	v_cndmask_b32_e64 v134, 0, v91, s[8:9]
	v_add_f32_e32 v90, v134, v90
	v_cndmask_b32_e64 v134, 0, v93, s[10:11]
	v_add_f32_e32 v90, v134, v90
	s_mov_b64 s[14:15], 0

.LBB0_2183:
	s_add_u32 s0, s48, s34
	s_addc_u32 s1, s49, s35
	s_add_u32 s58, s39, s34
	s_addc_u32 s59, s37, s35
	s_add_u32 s42, s58, s44
	s_addc_u32 s43, s59, 0
	s_add_u32 s60, s42, 0x16e40800
	s_addc_u32 s61, s43, 0
	s_and_b32 s57, s56, 1
	s_cmp_eq_u32 s57, 0
	s_cselect_b64 s[42:43], -1, 0
	s_and_b64 s[62:63], s[42:43], exec
	s_cselect_b32 s62, 0xf0, s52
	v_and_b32_e32 v136, 63, v154
	v_lshl_add_u32 v136, v136, 2, s62
	ds_read2st64_b32 v[72:73], v136 offset1:1
	v_lshl_add_u64 v[74:75], s[0:1], 0, v[102:103]
	ds_read2st64_b32 v[80:81], v136 offset0:4 offset1:5
	global_load_dwordx4 v[92:95], v[74:75], off
	global_load_dwordx4 v[96:99], v[74:75], off offset:1024
	ds_read2st64_b32 v[132:133], v136 offset0:2 offset1:3
	v_lshl_add_u64 v[82:83], s[60:61], 0, v[104:105]
	s_waitcnt lgkmcnt(2)
	v_mfma_f32_16x16x4_f32 v[68:71], v72, v155, 0
	v_add_co_u32_e64 v72, s[0:1], s50, v74
	v_mfma_f32_16x16x4_f32 v[68:71], v73, v164, v[68:71]
	s_nop 0
	v_addc_co_u32_e64 v73, s[0:1], 0, v75, s[0:1]
	global_load_dwordx4 v[84:87], v[72:73], off
	global_load_dwordx4 v[88:91], v[72:73], off offset:1024
	v_add_co_u32_e64 v72, s[0:1], s45, v82
	s_nop 1
	v_addc_co_u32_e64 v73, s[0:1], 0, v83, s[0:1]
	s_waitcnt lgkmcnt(0)
	v_mfma_f32_16x16x4_f32 v[124:127], v132, v165, v[68:71]
	v_add_co_u32_e64 v134, s[0:1], s50, v82
	global_load_dwordx4 v[68:71], v[82:83], off
	s_nop 0
	global_load_dwordx4 v[72:75], v[72:73], off
	v_addc_co_u32_e64 v135, s[0:1], 0, v83, s[0:1]
	v_mfma_f32_16x16x4_f32 v[76:79], v80, v155, 0
	v_add_co_u32_e64 v80, s[0:1], s51, v82
	v_mfma_f32_16x16x4_f32 v[124:127], v133, v166, v[124:127]
	v_mfma_f32_16x16x4_f32 v[128:131], v81, v164, v[76:79]
	v_addc_co_u32_e64 v81, s[0:1], 0, v83, s[0:1]
	s_nop 5
	global_load_dwordx4 v[76:79], v[134:135], off
	s_nop 0
	global_load_dwordx4 v[80:83], v[80:81], off
	ds_read2st64_b32 v[134:135], v136 offset0:6 offset1:7
	v_add_f32_e32 v124, v167, v124
	v_min_f32_e32 v137, 0, v124
	v_mul_f32_e64 v124, |v124|, s53
	v_exp_f32_e32 v124, v124
	v_add_f32_e32 v126, v167, v126
	v_mul_f32_e64 v133, |v126|, s53
	v_exp_f32_e32 v133, v133
	v_add_f32_e32 v124, 1.0, v124
	v_log_f32_e32 v124, v124
	s_waitcnt lgkmcnt(0)
	v_mfma_f32_16x16x4_f32 v[128:131], v134, v165, v[128:131]
	v_add_f32_e32 v133, 1.0, v133
	v_min_f32_e32 v139, 0, v126
	v_fmac_f32_e32 v137, 0xbf317218, v124
	v_log_f32_e32 v124, v133
	v_add_f32_e32 v134, v167, v127
	v_add_f32_e32 v125, v167, v125
	v_mul_f32_e64 v132, |v125|, s53
	v_fmac_f32_e32 v139, 0xbf317218, v124
	v_mul_f32_e64 v124, |v134|, s53
	v_min_f32_e32 v138, 0, v125
	v_exp_f32_e32 v140, v124
	v_mfma_f32_16x16x4_f32 v[124:127], v135, v166, v[128:131]
	v_exp_f32_e32 v132, v132
	v_add_f32_e32 v129, 1.0, v140
	v_log_f32_e32 v129, v129
	v_add_f32_e32 v132, 1.0, v132
	v_log_f32_e32 v132, v132
	v_min_f32_e32 v140, 0, v134
	s_nop 3
	v_add_f32_e32 v124, v167, v124
	v_mul_f32_e64 v128, |v124|, s53
	v_fmac_f32_e32 v138, 0xbf317218, v132
	v_exp_f32_e32 v128, v128
	ds_read2st64_b32 v[132:133], v136 offset0:8 offset1:9
	v_min_f32_e32 v141, 0, v124
	v_fmac_f32_e32 v140, 0xbf317218, v129
	v_add_f32_e32 v128, 1.0, v128
	v_log_f32_e32 v128, v128
	ds_read2st64_b32 v[134:135], v136 offset0:10 offset1:11
	v_add_f32_e32 v124, v167, v125
	v_mul_f32_e64 v125, |v124|, s53
	v_fmac_f32_e32 v141, 0xbf317218, v128
	s_waitcnt lgkmcnt(1)
	v_mfma_f32_16x16x4_f32 v[128:131], v132, v155, 0
	v_add_f32_e32 v132, v167, v126
	v_exp_f32_e32 v125, v125
	v_mul_f32_e64 v126, |v132|, s53
	v_exp_f32_e32 v126, v126
	v_min_f32_e32 v142, 0, v124
	v_add_f32_e32 v124, 1.0, v125
	v_add_f32_e32 v144, v167, v127
	v_mfma_f32_16x16x4_f32 v[128:131], v133, v164, v[128:131]
	v_log_f32_e32 v133, v124
	v_add_f32_e32 v124, 1.0, v126
	v_log_f32_e32 v143, v124
	v_mul_f32_e64 v145, |v144|, s53
	v_fmac_f32_e32 v142, 0xbf317218, v133
	s_waitcnt lgkmcnt(0)
	v_mfma_f32_16x16x4_f32 v[124:127], v134, v165, v[128:131]
	s_nop 2
	v_exp_f32_e32 v128, v145
	v_min_f32_e32 v145, 0, v132
	ds_read2st64_b32 v[132:133], v136 offset0:12 offset1:13
	v_fmac_f32_e32 v145, 0xbf317218, v143
	v_add_f32_e32 v128, 1.0, v128
	v_log_f32_e32 v128, v128
	v_min_f32_e32 v143, 0, v144
	v_mfma_f32_16x16x4_f32 v[124:127], v135, v166, v[124:127]
	v_fmac_f32_e32 v143, 0xbf317218, v128
	s_nop 8
	v_add_f32_e32 v124, v167, v124
	v_mul_f32_e64 v128, |v124|, s53
	v_exp_f32_e32 v134, v128
	s_waitcnt lgkmcnt(0)
	v_mfma_f32_16x16x4_f32 v[128:131], v132, v155, 0
	v_add_f32_e32 v125, v167, v125
	v_mul_f32_e64 v135, |v125|, s53
	v_exp_f32_e32 v132, v135
	v_min_f32_e32 v144, 0, v124
	v_add_f32_e32 v124, 1.0, v134
	ds_read2st64_b32 v[134:135], v136 offset0:14 offset1:15
	v_add_f32_e32 v132, 1.0, v132
	v_mfma_f32_16x16x4_f32 v[128:131], v133, v164, v[128:131]
	v_log_f32_e32 v132, v132
	v_log_f32_e32 v124, v124
	v_min_f32_e32 v133, 0, v125
	v_add_f32_e32 v146, v167, v127
	v_fmac_f32_e32 v133, 0xbf317218, v132
	v_add_f32_e32 v132, v167, v126
	v_fmac_f32_e32 v144, 0xbf317218, v124
	v_mul_f32_e64 v124, |v132|, s53
	v_exp_f32_e32 v136, v124
	s_waitcnt lgkmcnt(0)
	v_mfma_f32_16x16x4_f32 v[124:127], v134, v165, v[128:131]
	v_mul_f32_e64 v128, |v146|, s53
	v_exp_f32_e32 v128, v128
	v_add_f32_e32 v130, 1.0, v136
	v_log_f32_e32 v130, v130
	v_min_f32_e32 v129, 0, v132
	v_add_f32_e32 v128, 1.0, v128
	v_log_f32_e32 v128, v128
	v_mfma_f32_16x16x4_f32 v[124:127], v135, v166, v[124:127]
	v_fmac_f32_e32 v129, 0xbf317218, v130
	v_min_f32_e32 v130, 0, v146
	v_fmac_f32_e32 v130, 0xbf317218, v128
	s_nop 6
	v_add_f32_e32 v124, v167, v124
	v_mul_f32_e64 v131, |v124|, s53
	v_exp_f32_e32 v131, v131
	v_add_f32_e32 v125, v167, v125
	v_min_f32_e32 v124, 0, v124
	v_add_f32_e32 v126, v167, v126
	v_add_f32_e32 v128, 1.0, v131
	v_mul_f32_e64 v131, |v125|, s53
	v_log_f32_e32 v128, v128
	v_exp_f32_e32 v131, v131
	v_add_f32_e32 v127, v167, v127
	v_mul_f32_e64 v132, |v127|, s53
	v_fmac_f32_e32 v124, 0xbf317218, v128
	v_add_f32_e32 v128, 1.0, v131
	v_mul_f32_e64 v131, |v126|, s53
	v_log_f32_e32 v128, v128
	v_exp_f32_e32 v131, v131
	v_exp_f32_e32 v132, v132
	v_min_f32_e32 v125, 0, v125
	v_fmac_f32_e32 v125, 0xbf317218, v128
	v_add_f32_e32 v128, 1.0, v131
	v_add_f32_e32 v131, 1.0, v132
	v_log_f32_e32 v131, v131
	v_log_f32_e32 v128, v128
	v_min_f32_e32 v127, 0, v127
	v_min_f32_e32 v126, 0, v126
	v_fmac_f32_e32 v127, 0xbf317218, v131
	v_fmac_f32_e32 v126, 0xbf317218, v128
	v_fma_f32 v127, v127, s54, 0
	v_fmamk_f32 v126, v126, 0x3d800000, v127
	v_fmamk_f32 v125, v125, 0x3d800000, v126
	v_fmamk_f32 v124, v124, 0x3d800000, v125
	v_fmamk_f32 v128, v130, 0x3d800000, v124
	v_fmamk_f32 v129, v129, 0x3d800000, v128
	v_fmamk_f32 v130, v133, 0x3d800000, v129
	v_fmamk_f32 v131, v144, 0x3d800000, v130
	v_fmamk_f32 v132, v143, 0x3d800000, v131
	v_fmamk_f32 v133, v145, 0x3d800000, v132
	v_fmamk_f32 v134, v142, 0x3d800000, v133
	v_fmamk_f32 v135, v141, 0x3d800000, v134
	v_fmamk_f32 v136, v140, 0x3d800000, v135
	v_fmamk_f32 v139, v139, 0x3d800000, v136
	v_fmamk_f32 v138, v138, 0x3d800000, v139
	v_fmamk_f32 v137, v137, 0x3d800000, v138
	v_mov_b32_e32 v244, v137
	v_mov_b32_e32 v245, v137
	s_nop 1
	v_permlane16_swap_b32_e32 v244, v245
	v_mov_b32_e32 v246, v244
	v_mov_b32_e32 v247, v245
	s_nop 1
	v_permlane32_swap_b32_e32 v244, v246
	v_permlane32_swap_b32_e32 v245, v247
	v_mov_b32_e32 v140, v247
	v_mov_b32_e32 v141, v246
	v_mov_b32_e32 v142, v245
	s_waitcnt lgkmcnt(2)
	v_cndmask_b32_e64 v140, v140, 0, s[2:3]
	s_waitcnt lgkmcnt(1)
	v_cndmask_b32_e64 v141, 0, v141, s[4:5]
	v_add_f32_e32 v140, v141, v140
	s_waitcnt lgkmcnt(0)
	v_cndmask_b32_e64 v141, 0, v142, s[6:7]
	v_add_f32_e32 v140, v141, v140
	v_add_f32_e32 v137, v140, v137
	v_add_f32_e32 v138, v140, v138
	v_add_f32_e32 v124, v140, v124
	v_add_f32_e32 v125, v140, v125
	ds_write2st64_b32 v184, v137, v138 offset0:24 offset1:26
	v_add_f32_e32 v137, v140, v139
	v_add_f32_e32 v136, v140, v136
	v_add_f32_e32 v135, v140, v135
	v_add_f32_e32 v134, v140, v134
	v_add_f32_e32 v133, v140, v133
	v_add_f32_e32 v132, v140, v132
	v_add_f32_e32 v131, v140, v131
	v_add_f32_e32 v130, v140, v130
	v_add_f32_e32 v129, v140, v129
	v_add_f32_e32 v128, v140, v128
	ds_write2st64_b32 v184, v124, v125 offset0:48 offset1:50
	v_add_f32_e32 v124, v140, v126
	v_add_f32_e32 v125, v140, v127
	ds_write2st64_b32 v184, v137, v136 offset0:28 offset1:30
	ds_write2st64_b32 v184, v135, v134 offset0:32 offset1:34
	ds_write2st64_b32 v184, v133, v132 offset0:36 offset1:38
	ds_write2st64_b32 v184, v131, v130 offset0:40 offset1:42
	ds_write2st64_b32 v184, v129, v128 offset0:44 offset1:46
	ds_write2st64_b32 v184, v124, v125 offset0:52 offset1:54
	s_waitcnt lgkmcnt(0)
	s_barrier
	s_and_saveexec_b64 s[0:1], s[8:9]
	s_cbranch_execz .LBB0_2185
	ds_read_b32 v124, v175 offset:6144
	v_lshl_add_u32 v125, s57, 9, v175
	s_waitcnt lgkmcnt(0)
	v_mul_f32_e32 v255, 0x3fb8aa3b, v124
	v_exp_f32_e32 v255, v255
	s_nop 0
	ds_write_b32 v125, v255 offset:4096

.LBB0_2267:
	s_add_u32 s62, s92, s74
	s_addc_u32 s63, s94, s75
	s_add_u32 s49, s53, s74
	s_addc_u32 s61, s55, s75
	v_lshl_add_u64 v[70:71], s[62:63], 0, v[112:113]
	s_add_u32 s62, s49, s0
	v_add_co_u32_e32 v74, vcc, s72, v70
	s_addc_u32 s63, s61, 0
	s_nop 0
	v_addc_co_u32_e32 v75, vcc, 0, v71, vcc
	v_lshl_add_u64 v[86:87], s[62:63], 0, v[114:115]
	v_add_co_u32_e32 v78, vcc, s81, v86
	s_and_b32 s49, s95, 1
	s_add_i32 s89, s1, 0xf0
	v_addc_co_u32_e32 v79, vcc, 0, v87, vcc
	s_cmp_eq_u32 s49, 0
	v_add_co_u32_e32 v82, vcc, s72, v86
	s_cselect_b64 s[76:77], -1, 0
	s_nop 0
	v_addc_co_u32_e32 v83, vcc, 0, v87, vcc
	s_and_b64 s[62:63], s[76:77], exec
	global_load_dwordx4 v[94:97], v[70:71], off
	global_load_dwordx4 v[98:101], v[70:71], off offset:1024
	s_nop 0
	global_load_dwordx4 v[70:73], v[74:75], off
	global_load_dwordx4 v[90:93], v[74:75], off offset:1024
	s_cselect_b32 s61, 0xf0, s89
	global_load_dwordx4 v[74:77], v[86:87], off
	v_add_co_u32_e32 v86, vcc, s73, v86
	v_and_b32_e32 v137, 63, v154
	v_lshl_add_u32 v137, v137, 2, s61
	s_nop 0
	v_addc_co_u32_e32 v87, vcc, 0, v87, vcc
	global_load_dwordx4 v[78:81], v[78:79], off
	s_nop 0
	global_load_dwordx4 v[82:85], v[82:83], off
	s_nop 0
	global_load_dwordx4 v[86:89], v[86:87], off
	ds_read2st64_b32 v[108:109], v137 offset1:1
	ds_read2st64_b32 v[142:143], v137 offset0:2 offset1:3
	s_waitcnt lgkmcnt(1)
	v_mfma_f32_16x16x4_f32 v[138:141], v108, v102, 0
	ds_read2st64_b32 v[146:147], v137 offset0:8 offset1:9
	v_mfma_f32_16x16x4_f32 v[138:141], v109, v103, v[138:141]
	s_waitcnt lgkmcnt(1)
	v_mfma_f32_16x16x4_f32 v[138:141], v142, v104, v[138:141]
	v_mfma_f32_16x16x4_f32 v[138:141], v143, v105, v[138:141]
	ds_read2st64_b32 v[142:143], v137 offset0:4 offset1:5
	s_nop 8
	v_add_f32_e32 v108, v106, v138
	v_min_f32_e32 v107, 0, v108
	v_mul_f32_e64 v108, |v108|, s66
	v_exp_f32_e32 v108, v108
	v_add_f32_e32 v109, v106, v139
	v_add_f32_e32 v135, v106, v140
	v_add_f32_e32 v138, v106, v141
	v_add_f32_e32 v108, 1.0, v108
	v_log_f32_e32 v108, v108
	s_nop 0
	v_fmac_f32_e32 v107, 0xbf317218, v108
	v_min_f32_e32 v108, 0, v109
	v_mul_f32_e64 v109, |v109|, s66
	v_exp_f32_e32 v109, v109
	v_fma_f32 v107, v107, s67, 0
	v_add_f32_e32 v109, 1.0, v109
	v_log_f32_e32 v109, v109
	s_nop 0
	v_fmac_f32_e32 v108, 0xbf317218, v109
	v_min_f32_e32 v109, 0, v135
	v_mul_f32_e64 v135, |v135|, s66
	v_exp_f32_e32 v135, v135
	v_fmamk_f32 v108, v108, 0x3d800000, v107
	v_add_f32_e32 v135, 1.0, v135
	v_log_f32_e32 v135, v135
	s_nop 0
	v_fmac_f32_e32 v109, 0xbf317218, v135
	v_min_f32_e32 v135, 0, v138
	v_mul_f32_e64 v138, |v138|, s66
	v_exp_f32_e32 v138, v138
	v_fmamk_f32 v109, v109, 0x3d800000, v108
	v_add_f32_e32 v138, 1.0, v138
	v_log_f32_e32 v138, v138
	s_nop 0
	v_fmac_f32_e32 v135, 0xbf317218, v138
	s_waitcnt lgkmcnt(0)
	v_mfma_f32_16x16x4_f32 v[138:141], v142, v102, 0
	v_fmamk_f32 v135, v135, 0x3d800000, v109
	v_mfma_f32_16x16x4_f32 v[138:141], v143, v103, v[138:141]
	ds_read2st64_b32 v[142:143], v137 offset0:6 offset1:7
	s_waitcnt lgkmcnt(0)
	v_mfma_f32_16x16x4_f32 v[138:141], v142, v104, v[138:141]
	v_mfma_f32_16x16x4_f32 v[138:141], v143, v105, v[138:141]
	s_nop 9
	v_add_f32_e32 v142, v106, v138
	v_min_f32_e32 v138, 0, v142
	v_mul_f32_e64 v142, |v142|, s66
	v_exp_f32_e32 v142, v142
	s_nop 0
	v_add_f32_e32 v142, 1.0, v142
	v_log_f32_e32 v142, v142
	s_nop 0
	v_fmac_f32_e32 v138, 0xbf317218, v142
	v_add_f32_e32 v142, v106, v139
	v_min_f32_e32 v139, 0, v142
	v_mul_f32_e64 v142, |v142|, s66
	v_exp_f32_e32 v142, v142
	s_nop 0
	v_add_f32_e32 v142, 1.0, v142
	v_log_f32_e32 v142, v142
	s_nop 0
	v_fmac_f32_e32 v139, 0xbf317218, v142
	v_add_f32_e32 v142, v106, v140
	v_min_f32_e32 v140, 0, v142
	v_mul_f32_e64 v142, |v142|, s66
	v_exp_f32_e32 v142, v142
	s_nop 0
	v_add_f32_e32 v142, 1.0, v142
	v_log_f32_e32 v142, v142
	s_nop 0
	v_fmac_f32_e32 v140, 0xbf317218, v142
	v_add_f32_e32 v142, v106, v141
	v_min_f32_e32 v141, 0, v142
	v_mul_f32_e64 v142, |v142|, s66
	v_exp_f32_e32 v142, v142
	s_nop 0
	v_add_f32_e32 v142, 1.0, v142
	v_log_f32_e32 v142, v142
	s_nop 0
	v_fmac_f32_e32 v141, 0xbf317218, v142
	v_mfma_f32_16x16x4_f32 v[142:145], v146, v102, 0
	v_mfma_f32_16x16x4_f32 v[142:145], v147, v103, v[142:145]
	ds_read2st64_b32 v[146:147], v137 offset0:10 offset1:11
	s_waitcnt lgkmcnt(0)
	v_mfma_f32_16x16x4_f32 v[142:145], v146, v104, v[142:145]
	v_mfma_f32_16x16x4_f32 v[142:145], v147, v105, v[142:145]
	ds_read2st64_b32 v[146:147], v137 offset0:12 offset1:13
	s_nop 8
	v_add_f32_e32 v142, v106, v142
	v_min_f32_e32 v148, 0, v142
	v_mul_f32_e64 v142, |v142|, s66
	v_exp_f32_e32 v142, v142
	s_nop 0
	v_add_f32_e32 v142, 1.0, v142
	v_log_f32_e32 v142, v142
	s_nop 0
	v_fmac_f32_e32 v148, 0xbf317218, v142
	v_add_f32_e32 v142, v106, v143
	v_min_f32_e32 v149, 0, v142
	v_mul_f32_e64 v142, |v142|, s66
	v_exp_f32_e32 v142, v142
	s_nop 0
	v_add_f32_e32 v142, 1.0, v142
	v_log_f32_e32 v142, v142
	s_nop 0
	v_fmac_f32_e32 v149, 0xbf317218, v142
	v_add_f32_e32 v142, v106, v144
	v_min_f32_e32 v150, 0, v142
	v_mul_f32_e64 v142, |v142|, s66
	v_exp_f32_e32 v142, v142
	s_nop 0
	v_add_f32_e32 v142, 1.0, v142
	v_log_f32_e32 v142, v142
	s_nop 0
	v_fmac_f32_e32 v150, 0xbf317218, v142
	v_add_f32_e32 v142, v106, v145
	v_min_f32_e32 v151, 0, v142
	v_mul_f32_e64 v142, |v142|, s66
	v_exp_f32_e32 v142, v142
	s_nop 0
	v_add_f32_e32 v142, 1.0, v142
	v_log_f32_e32 v142, v142
	s_nop 0
	v_fmac_f32_e32 v151, 0xbf317218, v142
	s_waitcnt lgkmcnt(0)
	v_mfma_f32_16x16x4_f32 v[142:145], v146, v102, 0
	v_mfma_f32_16x16x4_f32 v[142:145], v147, v103, v[142:145]
	ds_read2st64_b32 v[146:147], v137 offset0:14 offset1:15
	s_waitcnt lgkmcnt(0)
	v_mfma_f32_16x16x4_f32 v[142:145], v146, v104, v[142:145]
	v_mfma_f32_16x16x4_f32 v[142:145], v147, v105, v[142:145]
	s_nop 9
	v_add_f32_e32 v137, v106, v142
	v_min_f32_e32 v142, 0, v137
	v_mul_f32_e64 v137, |v137|, s66
	v_exp_f32_e32 v137, v137
	s_nop 0
	v_add_f32_e32 v137, 1.0, v137
	v_log_f32_e32 v137, v137
	s_nop 0
	v_fmac_f32_e32 v142, 0xbf317218, v137
	v_add_f32_e32 v137, v106, v143
	v_min_f32_e32 v143, 0, v137
	v_mul_f32_e64 v137, |v137|, s66
	v_exp_f32_e32 v137, v137
	s_nop 0
	v_add_f32_e32 v137, 1.0, v137
	v_log_f32_e32 v137, v137
	s_nop 0
	v_fmac_f32_e32 v143, 0xbf317218, v137
	v_add_f32_e32 v137, v106, v144
	v_min_f32_e32 v144, 0, v137
	v_mul_f32_e64 v137, |v137|, s66
	v_exp_f32_e32 v137, v137
	s_nop 0
	v_add_f32_e32 v137, 1.0, v137
	v_log_f32_e32 v137, v137
	s_nop 0
	v_fmac_f32_e32 v144, 0xbf317218, v137
	v_add_f32_e32 v137, v106, v145
	v_min_f32_e32 v145, 0, v137
	v_mul_f32_e64 v137, |v137|, s66
	v_exp_f32_e32 v137, v137
	s_nop 0
	v_add_f32_e32 v137, 1.0, v137
	v_log_f32_e32 v137, v137
	s_nop 0
	v_fmac_f32_e32 v145, 0xbf317218, v137
	v_fmamk_f32 v137, v138, 0x3d800000, v135
	v_fmamk_f32 v138, v139, 0x3d800000, v137
	v_fmamk_f32 v139, v140, 0x3d800000, v138
	v_fmamk_f32 v140, v141, 0x3d800000, v139
	v_fmamk_f32 v141, v148, 0x3d800000, v140
	v_fmamk_f32 v146, v149, 0x3d800000, v141
	v_fmamk_f32 v147, v150, 0x3d800000, v146
	v_fmamk_f32 v148, v151, 0x3d800000, v147
	v_fmamk_f32 v142, v142, 0x3d800000, v148
	v_fmamk_f32 v143, v143, 0x3d800000, v142
	v_fmamk_f32 v144, v144, 0x3d800000, v143
	v_fmamk_f32 v145, v145, 0x3d800000, v144
	v_mov_b32_e32 v244, v145
	v_mov_b32_e32 v245, v145
	s_nop 1
	v_permlane16_swap_b32_e32 v244, v245
	v_mov_b32_e32 v246, v244
	v_mov_b32_e32 v247, v245
	s_nop 1
	v_permlane32_swap_b32_e32 v244, v246
	v_permlane32_swap_b32_e32 v245, v247
	v_mov_b32_e32 v149, v244
	v_mov_b32_e32 v150, v245
	v_mov_b32_e32 v151, v246
	s_waitcnt lgkmcnt(2)
	v_cndmask_b32_e64 v149, v149, 0, s[4:5]
	s_waitcnt lgkmcnt(1)
	v_cndmask_b32_e64 v150, 0, v150, s[6:7]
	v_add_f32_e32 v149, v149, v150
	s_waitcnt lgkmcnt(0)
	v_cndmask_b32_e64 v150, 0, v151, s[8:9]
	v_add_f32_e32 v149, v149, v150
	v_add_f32_e32 v107, v107, v149
	v_add_f32_e32 v108, v108, v149
	ds_write2st64_b32 v204, v107, v108 offset0:24 offset1:26
	v_add_f32_e32 v107, v109, v149
	v_add_f32_e32 v108, v135, v149
	ds_write2st64_b32 v204, v107, v108 offset0:28 offset1:30
	v_add_f32_e32 v107, v137, v149
	v_add_f32_e32 v108, v138, v149
	ds_write2st64_b32 v204, v107, v108 offset0:32 offset1:34
	v_add_f32_e32 v107, v139, v149
	v_add_f32_e32 v108, v140, v149
	ds_write2st64_b32 v204, v107, v108 offset0:36 offset1:38
	v_add_f32_e32 v107, v141, v149
	v_add_f32_e32 v108, v146, v149
	ds_write2st64_b32 v204, v107, v108 offset0:40 offset1:42
	v_add_f32_e32 v107, v149, v147
	v_add_f32_e32 v108, v149, v148
	ds_write2st64_b32 v204, v107, v108 offset0:44 offset1:46
	v_add_f32_e32 v107, v149, v142
	v_add_f32_e32 v108, v149, v143
	ds_write2st64_b32 v204, v107, v108 offset0:48 offset1:50
	v_add_f32_e32 v107, v149, v144
	v_add_f32_e32 v108, v149, v145
	ds_write2st64_b32 v204, v107, v108 offset0:52 offset1:54
	s_waitcnt lgkmcnt(0)
	s_barrier
	s_and_saveexec_b64 s[62:63], s[10:11]
	s_cbranch_execz .LBB0_2269
	ds_read_b32 v107, v181 offset:38400
	v_lshl_add_u32 v108, s49, 9, v181
	s_waitcnt lgkmcnt(0)
	v_mul_f32_e32 v255, 0x3fb8aa3b, v107
	v_exp_f32_e32 v255, v255
	s_nop 0
	ds_write_b32 v108, v255 offset:4096

.LBB0_2283:
	s_add_u32 s60, s70, s58
	s_addc_u32 s61, s71, s59
	s_add_u32 s49, s64, s58
	s_addc_u32 s69, s65, s59
	s_add_u32 s53, s49, s0
	v_lshl_add_u64 v[70:71], s[60:61], 0, v[112:113]
	s_addc_u32 s61, s69, 0
	s_add_u32 s60, s53, 0xafc0800
	v_add_co_u32_e32 v74, vcc, s72, v70
	s_addc_u32 s61, s61, 0
	s_nop 0
	v_addc_co_u32_e32 v75, vcc, 0, v71, vcc
	v_lshl_add_u64 v[86:87], s[60:61], 0, v[114:115]
	v_add_co_u32_e32 v78, vcc, s81, v86
	s_and_b32 s68, s74, 1
	s_nop 0
	v_addc_co_u32_e32 v79, vcc, 0, v87, vcc
	s_cmp_eq_u32 s68, 0
	v_add_co_u32_e32 v82, vcc, s72, v86
	s_cselect_b64 s[60:61], -1, 0
	s_nop 0
	v_addc_co_u32_e32 v83, vcc, 0, v87, vcc
	s_and_b64 s[62:63], s[60:61], exec
	global_load_dwordx4 v[94:97], v[70:71], off
	global_load_dwordx4 v[98:101], v[70:71], off offset:1024
	s_nop 0
	global_load_dwordx4 v[70:73], v[74:75], off
	global_load_dwordx4 v[90:93], v[74:75], off offset:1024
	s_cselect_b32 s53, 0xf0, s89
	global_load_dwordx4 v[74:77], v[86:87], off
	v_add_co_u32_e32 v86, vcc, s73, v86
	v_and_b32_e32 v105, 63, v154
	v_lshl_add_u32 v105, v105, 2, s53
	s_nop 0
	v_addc_co_u32_e32 v87, vcc, 0, v87, vcc
	global_load_dwordx4 v[78:81], v[78:79], off
	s_nop 0
	global_load_dwordx4 v[82:85], v[82:83], off
	s_nop 0
	global_load_dwordx4 v[86:89], v[86:87], off
	ds_read2st64_b32 v[102:103], v105 offset1:1
	ds_read2st64_b32 v[140:141], v105 offset0:2 offset1:3
	s_waitcnt vmcnt(12) lgkmcnt(1)
	v_mfma_f32_16x16x4_f32 v[106:109], v102, v223, 0
	ds_read2st64_b32 v[144:145], v105 offset0:8 offset1:9
	s_waitcnt vmcnt(11)
	v_mfma_f32_16x16x4_f32 v[106:109], v103, v224, v[106:109]
	s_waitcnt vmcnt(10) lgkmcnt(1)
	v_mfma_f32_16x16x4_f32 v[106:109], v140, v225, v[106:109]
	s_waitcnt vmcnt(9)
	v_mfma_f32_16x16x4_f32 v[106:109], v141, v226, v[106:109]
	ds_read2st64_b32 v[140:141], v105 offset0:4 offset1:5
	s_waitcnt vmcnt(8)
	s_nop 7
	v_add_f32_e32 v102, v227, v106
	v_min_f32_e32 v0, 0, v102
	v_mul_f32_e64 v102, |v102|, s66
	v_exp_f32_e32 v102, v102
	v_add_f32_e32 v103, v227, v107
	v_add_f32_e32 v104, v227, v108
	v_add_f32_e32 v106, v227, v109
	v_add_f32_e32 v102, 1.0, v102
	v_log_f32_e32 v102, v102
	s_nop 0
	v_fmac_f32_e32 v0, 0xbf317218, v102
	v_min_f32_e32 v102, 0, v103
	v_mul_f32_e64 v103, |v103|, s66
	v_exp_f32_e32 v103, v103
	s_nop 0
	v_add_f32_e32 v103, 1.0, v103
	v_log_f32_e32 v103, v103
	s_nop 0
	v_fmac_f32_e32 v102, 0xbf317218, v103
	v_min_f32_e32 v103, 0, v104
	v_mul_f32_e64 v104, |v104|, s66
	v_exp_f32_e32 v104, v104
	s_nop 0
	v_add_f32_e32 v104, 1.0, v104
	v_log_f32_e32 v104, v104
	s_nop 0
	v_fmac_f32_e32 v103, 0xbf317218, v104
	v_min_f32_e32 v104, 0, v106
	v_mul_f32_e64 v106, |v106|, s66
	v_exp_f32_e32 v106, v106
	s_nop 0
	v_add_f32_e32 v106, 1.0, v106
	v_log_f32_e32 v106, v106
	s_nop 0
	v_fmac_f32_e32 v104, 0xbf317218, v106
	s_waitcnt lgkmcnt(0)
	v_mfma_f32_16x16x4_f32 v[106:109], v140, v223, 0
	v_mfma_f32_16x16x4_f32 v[106:109], v141, v224, v[106:109]
	ds_read2st64_b32 v[140:141], v105 offset0:6 offset1:7
	s_waitcnt lgkmcnt(0)
	v_mfma_f32_16x16x4_f32 v[106:109], v140, v225, v[106:109]
	v_mfma_f32_16x16x4_f32 v[106:109], v141, v226, v[106:109]
	v_mfma_f32_16x16x4_f32 v[140:143], v144, v223, 0
	s_nop 8
	v_add_f32_e32 v135, v227, v106
	v_min_f32_e32 v106, 0, v135
	v_mul_f32_e64 v135, |v135|, s66
	v_exp_f32_e32 v135, v135
	s_nop 0
	v_add_f32_e32 v135, 1.0, v135
	v_log_f32_e32 v135, v135
	v_mfma_f32_16x16x4_f32 v[140:143], v145, v224, v[140:143]
	ds_read2st64_b32 v[144:145], v105 offset0:10 offset1:11
	v_fmac_f32_e32 v106, 0xbf317218, v135
	v_add_f32_e32 v135, v227, v107
	v_min_f32_e32 v107, 0, v135
	v_mul_f32_e64 v135, |v135|, s66
	v_exp_f32_e32 v135, v135
	s_waitcnt lgkmcnt(0)
	v_mfma_f32_16x16x4_f32 v[140:143], v144, v225, v[140:143]
	v_add_f32_e32 v135, 1.0, v135
	v_log_f32_e32 v135, v135
	s_nop 0
	v_fmac_f32_e32 v107, 0xbf317218, v135
	v_add_f32_e32 v135, v227, v108
	v_min_f32_e32 v108, 0, v135
	v_mul_f32_e64 v135, |v135|, s66
	v_exp_f32_e32 v135, v135
	v_mfma_f32_16x16x4_f32 v[140:143], v145, v226, v[140:143]
	ds_read2st64_b32 v[144:145], v105 offset0:12 offset1:13
	v_add_f32_e32 v135, 1.0, v135
	v_log_f32_e32 v135, v135
	s_nop 0
	v_fmac_f32_e32 v108, 0xbf317218, v135
	v_add_f32_e32 v135, v227, v109
	v_min_f32_e32 v109, 0, v135
	v_mul_f32_e64 v135, |v135|, s66
	v_exp_f32_e32 v135, v135
	s_nop 0
	v_add_f32_e32 v135, 1.0, v135
	v_log_f32_e32 v135, v135
	s_nop 0
	v_fmac_f32_e32 v109, 0xbf317218, v135
	v_add_f32_e32 v135, v227, v140
	v_min_f32_e32 v137, 0, v135
	v_mul_f32_e64 v135, |v135|, s66
	v_exp_f32_e32 v135, v135
	s_nop 0
	v_add_f32_e32 v135, 1.0, v135
	v_log_f32_e32 v135, v135
	s_nop 0
	v_fmac_f32_e32 v137, 0xbf317218, v135
	v_add_f32_e32 v135, v227, v141
	v_min_f32_e32 v146, 0, v135
	v_mul_f32_e64 v135, |v135|, s66
	v_exp_f32_e32 v135, v135
	s_nop 0
	v_add_f32_e32 v135, 1.0, v135
	v_log_f32_e32 v135, v135
	s_nop 0
	v_fmac_f32_e32 v146, 0xbf317218, v135
	v_add_f32_e32 v135, v227, v142
	v_min_f32_e32 v147, 0, v135
	v_mul_f32_e64 v135, |v135|, s66
	v_exp_f32_e32 v135, v135
	s_nop 0
	v_add_f32_e32 v135, 1.0, v135
	v_log_f32_e32 v135, v135
	s_nop 0
	v_fmac_f32_e32 v147, 0xbf317218, v135
	v_add_f32_e32 v135, v227, v143
	s_waitcnt lgkmcnt(0)
	v_mfma_f32_16x16x4_f32 v[140:143], v144, v223, 0
	v_min_f32_e32 v148, 0, v135
	v_mul_f32_e64 v135, |v135|, s66
	v_exp_f32_e32 v135, v135
	s_nop 0
	v_add_f32_e32 v135, 1.0, v135
	v_mfma_f32_16x16x4_f32 v[140:143], v145, v224, v[140:143]
	ds_read2st64_b32 v[144:145], v105 offset0:14 offset1:15
	v_log_f32_e32 v135, v135
	s_nop 0
	v_fmac_f32_e32 v148, 0xbf317218, v135
	s_waitcnt lgkmcnt(0)
	v_mfma_f32_16x16x4_f32 v[140:143], v144, v225, v[140:143]
	v_mfma_f32_16x16x4_f32 v[140:143], v145, v226, v[140:143]
	s_nop 9
	v_add_f32_e32 v105, v227, v140
	v_min_f32_e32 v135, 0, v105
	v_mul_f32_e64 v105, |v105|, s66
	v_exp_f32_e32 v105, v105
	s_nop 0
	v_add_f32_e32 v105, 1.0, v105
	v_log_f32_e32 v105, v105
	s_nop 0
	v_fmac_f32_e32 v135, 0xbf317218, v105
	v_add_f32_e32 v105, v227, v141
	v_min_f32_e32 v140, 0, v105
	v_mul_f32_e64 v105, |v105|, s66
	v_exp_f32_e32 v105, v105
	s_nop 0
	v_add_f32_e32 v105, 1.0, v105
	v_log_f32_e32 v105, v105
	s_nop 0
	v_fmac_f32_e32 v140, 0xbf317218, v105
	v_add_f32_e32 v105, v227, v142
	v_min_f32_e32 v141, 0, v105
	v_mul_f32_e64 v105, |v105|, s66
	v_exp_f32_e32 v105, v105
	s_nop 0
	v_add_f32_e32 v105, 1.0, v105
	v_log_f32_e32 v105, v105
	s_nop 0
	v_fmac_f32_e32 v141, 0xbf317218, v105
	v_add_f32_e32 v105, v227, v143
	v_min_f32_e32 v142, 0, v105
	v_mul_f32_e64 v105, |v105|, s66
	v_exp_f32_e32 v105, v105
	s_nop 0
	v_add_f32_e32 v105, 1.0, v105
	v_log_f32_e32 v105, v105
	s_nop 0
	v_fmac_f32_e32 v142, 0xbf317218, v105
	v_fma_f32 v105, v142, s67, 0
	v_fmamk_f32 v141, v141, 0x3d800000, v105
	v_fmamk_f32 v140, v140, 0x3d800000, v141
	v_fmamk_f32 v135, v135, 0x3d800000, v140
	v_fmamk_f32 v142, v148, 0x3d800000, v135
	v_fmamk_f32 v143, v147, 0x3d800000, v142
	v_fmamk_f32 v144, v146, 0x3d800000, v143
	v_fmamk_f32 v137, v137, 0x3d800000, v144
	v_fmamk_f32 v109, v109, 0x3d800000, v137
	v_fmamk_f32 v108, v108, 0x3d800000, v109
	v_fmamk_f32 v107, v107, 0x3d800000, v108
	v_fmamk_f32 v106, v106, 0x3d800000, v107
	v_fmamk_f32 v104, v104, 0x3d800000, v106
	v_fmamk_f32 v103, v103, 0x3d800000, v104
	v_fmamk_f32 v102, v102, 0x3d800000, v103
	v_fmamk_f32 v0, v0, 0x3d800000, v102
	v_mov_b32_e32 v244, v0
	v_mov_b32_e32 v245, v0
	s_nop 1
	v_permlane16_swap_b32_e32 v244, v245
	v_mov_b32_e32 v246, v244
	v_mov_b32_e32 v247, v245
	s_nop 1
	v_permlane32_swap_b32_e32 v244, v246
	v_permlane32_swap_b32_e32 v245, v247
	v_mov_b32_e32 v146, v246
	v_mov_b32_e32 v147, v247
	v_mov_b32_e32 v145, v245
	s_waitcnt lgkmcnt(2)
	v_cndmask_b32_e64 v146, 0, v146, s[28:29]
	s_waitcnt lgkmcnt(1)
	v_cndmask_b32_e64 v147, v147, 0, s[8:9]
	v_add_f32_e32 v146, v146, v147
	s_waitcnt lgkmcnt(0)
	v_cndmask_b32_e64 v145, 0, v145, s[4:5]
	v_add_f32_e32 v145, v145, v146
	v_add_f32_e32 v0, v145, v0
	v_add_f32_e32 v102, v145, v102
	ds_write2st64_b32 v204, v0, v102 offset0:24 offset1:26
	v_add_f32_e32 v0, v145, v103
	v_add_f32_e32 v102, v145, v104
	ds_write2st64_b32 v204, v0, v102 offset0:28 offset1:30
	v_add_f32_e32 v0, v145, v106
	v_add_f32_e32 v102, v145, v107
	ds_write2st64_b32 v204, v0, v102 offset0:32 offset1:34
	v_add_f32_e32 v0, v145, v108
	v_add_f32_e32 v102, v145, v109
	ds_write2st64_b32 v204, v0, v102 offset0:36 offset1:38
	v_add_f32_e32 v0, v145, v137
	v_add_f32_e32 v102, v145, v144
	ds_write2st64_b32 v204, v0, v102 offset0:40 offset1:42
	v_add_f32_e32 v0, v145, v143
	v_add_f32_e32 v102, v145, v142
	ds_write2st64_b32 v204, v0, v102 offset0:44 offset1:46
	v_add_f32_e32 v0, v145, v135
	v_add_f32_e32 v102, v145, v140
	ds_write2st64_b32 v204, v0, v102 offset0:48 offset1:50
	v_add_f32_e32 v0, v145, v141
	v_add_f32_e32 v102, v145, v105
	ds_write2st64_b32 v204, v0, v102 offset0:52 offset1:54
	s_waitcnt lgkmcnt(0)
	s_barrier
	s_and_saveexec_b64 s[62:63], s[10:11]
	s_cbranch_execz .LBB0_2285
	ds_read_b32 v0, v181 offset:6144
	v_lshl_add_u32 v102, s68, 9, v181
	s_waitcnt lgkmcnt(0)
	v_mul_f32_e32 v255, 0x3fb8aa3b, v0
	v_exp_f32_e32 v255, v255
	s_nop 0
	ds_write_b32 v102, v255 offset:4096
